# prep LRU epilogue: per-channel softplus(-lambda) computed once per workgroup and reused across its row blocks (dead code removed from the fast path)
# speedup vs baseline: 1.0494x; 1.0019x over previous
; __device__ __forceinline__ float sigmoid_(float x) { return __builtin_amdgcn_rcpf(1.f + __expf(-x)); }
; __device__ __forceinline__ float softplus_(float x) { return fmaxf(x, 0.f) + log1pf(__expf(-fabsf(x))); }
; __device__ __forceinline__ void prep_phase(const Params& P, float* L, int l) {
;     ...
;         {
;             const int tt = wave & 3, d = wave >> 2;
;             f32x4 acc[2][4];
; #pragma unroll
;             for (int g2 = 0; g2 < 2; ++g2)
; #pragma unroll
;                 for (int jt = 0; jt < 4; ++jt) acc[g2][jt] = (f32x4){0.f, 0.f, 0.f, 0.f};
; #pragma unroll
;             for (int ks = 0; ks < 2; ++ks) {
;                 const bf16x8_t a = *(const bf16x8_t*)&xb[(tt * 16 + fr) * 72 + ks * 32 + fq * 8];
; #pragma unroll
;                 for (int g2 = 0; g2 < 2; ++g2)
; #pragma unroll
;                     for (int jt = 0; jt < 4; ++jt) { const bf16x8_t bq = *(const bf16x8_t*)&WT[((d * 2 + g2) * 64 + jt * 16 + fr) * 72 + ks * 32 + fq * 8];
;                         acc[g2][jt] = __builtin_amdgcn_mfma_f32_16x16x32_bf16(a, bq, acc[g2][jt], 0, 0, 0); }
;             }
; #pragma unroll
;             for (int jt = 0; jt < 4; ++jt) {
;                 const int j = jt * 16 + fr, c = h * 64 + j;
;                 const float ba1 = P.lru_ba[(size_t)(l * 2 + d) * 512 + c], bx1 = P.lru_bx[(size_t)(l * 2 + d) * 512 + c], sp = softplus_(-P.lru_lambda[(size_t)(l * 2 + d) * 512 + c]);
; #pragma unroll
;                 for (int jj = 0; jj < 4; ++jj) {
;                     const int t = tt * 16 + 4 * fq + jj, row = row0 + t;
;                     const float rg = sigmoid_(acc[0][jt][jj] + ba1), ig = sigmoid_(acc[1][jt][jj] + bx1);
;                     const float la = -8.f * rg * sp;
;                     const float a_ = __expf(la); LA[((size_t)d * MALL + row) * 512 + c] = a_;
.LBB0_258:
	s_or_b64 exec, exec, s[12:13]
	s_waitcnt lgkmcnt(0)
	s_barrier
	ds_read_b128 v[4:7], v54 offset:36864
	ds_read_b128 v[8:11], v64
	ds_read_b128 v[20:23], v64 offset:6912
	s_waitcnt lgkmcnt(0)
	v_mfma_f32_16x16x32_bf16 v[24:27], v[4:7], v[20:23], 0
	ds_read_b128 v[20:23], v64 offset:9216
	ds_read_b128 v[12:15], v64 offset:2304
	ds_read_b128 v[16:19], v64 offset:4608
	s_waitcnt lgkmcnt(0)
	v_mfma_f32_16x16x32_bf16 v[32:35], v[4:7], v[20:23], 0
	ds_read_b128 v[20:23], v64 offset:11520
	v_or_b32_e32 v2, s58, v53
	v_readlane_b32 s16, v254, 62
	s_waitcnt lgkmcnt(0)
	v_mfma_f32_16x16x32_bf16 v[42:45], v[4:7], v[20:23], 0
	ds_read_b128 v[20:23], v64 offset:13824
	v_readlane_b32 s60, v254, 54
	v_readlane_b32 s28, v255, 10
	s_waitcnt vmcnt(0) lgkmcnt(0)
	s_cmp_eq_u32 s101, 0
	s_cbranch_scc1 .Lprepe_fast
	v_mfma_f32_16x16x32_bf16 v[46:49], v[4:7], v[20:23], 0
	ds_read_b128 v[20:23], v64 offset:16128
	v_readlane_b32 s29, v255, 11
	v_readlane_b32 s61, v254, 55
	v_mfma_f32_16x16x32_bf16 v[8:11], v[4:7], v[8:11], 0
	v_readlane_b32 s62, v254, 56
	v_readlane_b32 s63, v254, 57
	s_mov_b32 s16, 0xbfb8aa3b
	v_mfma_f32_16x16x32_bf16 v[12:15], v[4:7], v[12:15], 0
	v_readlane_b32 s17, v254, 63
	s_mov_b32 s17, 0x3f2aaaab
	v_readlane_b32 s19, v255, 1
	v_mfma_f32_16x16x32_bf16 v[16:19], v[4:7], v[16:19], 0
	s_mov_b32 s19, 0x3f317218
	s_mov_b32 s3, 0x7f800000
	v_readlane_b32 s20, v255, 2
	s_waitcnt lgkmcnt(0)
	v_mfma_f32_16x16x32_bf16 v[66:69], v[4:7], v[20:23], 0
	ds_read_b128 v[70:73], v54 offset:36928
	ds_read_b128 v[4:7], v64 offset:64
	s_mov_b32 s20, 0x33800000
	v_or_b32_e32 v38, s49, v55
	s_waitcnt lgkmcnt(0)
	v_mfma_f32_16x16x32_bf16 v[28:31], v[70:73], v[4:7], v[8:11]
	ds_read_b128 v[4:7], v64 offset:2368
	s_nop 1
	ds_read_b128 v[8:11], v64 offset:9280
	v_readlane_b32 s18, v255, 0
	s_waitcnt lgkmcnt(1)
	v_mfma_f32_16x16x32_bf16 v[20:23], v[70:73], v[4:7], v[12:15]
	ds_read_b128 v[4:7], v64 offset:4672
	s_mov_b32 s18, 0xf800000
	v_readlane_b32 s56, v255, 30
	s_waitcnt lgkmcnt(1)
	v_mfma_f32_16x16x32_bf16 v[32:35], v[70:73], v[8:11], v[32:35]
	ds_read_b128 v[8:11], v64 offset:11584
	v_readlane_b32 s57, v255, 31
	v_readlane_b32 s21, v255, 3
	s_waitcnt lgkmcnt(1)
	v_mfma_f32_16x16x32_bf16 v[12:15], v[70:73], v[4:7], v[16:19]
	ds_read_b128 v[4:7], v64 offset:6976
	v_readlane_b32 s22, v255, 4
	v_readlane_b32 s23, v255, 5
	s_waitcnt lgkmcnt(0)
	v_mfma_f32_16x16x32_bf16 v[4:7], v[70:73], v[4:7], v[24:27]
	v_readlane_b32 s24, v255, 6
	v_readlane_b32 s25, v255, 7
	v_readlane_b32 s26, v255, 8
	v_mfma_f32_16x16x32_bf16 v[24:27], v[70:73], v[8:11], v[42:45]
	ds_read_b128 v[8:11], v64 offset:13888
	v_readlane_b32 s27, v255, 9
	v_readlane_b32 s30, v255, 12
	v_or_b32_e32 v42, s80, v2
	v_mov_b32_e32 v43, s81
	v_lshlrev_b64 v[44:45], 2, v[42:43]
	s_waitcnt lgkmcnt(0)
	v_mfma_f32_16x16x32_bf16 v[16:19], v[70:73], v[8:11], v[46:49]
	v_lshl_add_u64 v[42:43], s[28:29], 0, v[44:45]
	global_load_dword v42, v[42:43], off
	ds_read_b128 v[8:11], v64 offset:16192
	v_lshl_add_u64 v[46:47], s[60:61], 0, v[44:45]
	v_lshl_add_u64 v[44:45], s[62:63], 0, v[44:45]
	global_load_dword v43, v[44:45], off
	global_load_dword v41, v[46:47], off
	s_waitcnt lgkmcnt(0)
	v_mfma_f32_16x16x32_bf16 v[8:11], v[70:73], v[8:11], v[66:69]
	v_readlane_b32 s31, v255, 13
	v_readlane_b32 s64, v254, 58
	v_readlane_b32 s65, v254, 59
	v_readlane_b32 s66, v254, 60
	v_readlane_b32 s67, v254, 61
	s_waitcnt vmcnt(2)
	v_add_f32_e32 v28, v28, v42
	v_mul_f32_e32 v28, 0xbfb8aa3b, v28
	v_exp_f32_e32 v28, v28
	v_add_f32_e32 v29, v29, v42
	s_waitcnt vmcnt(1)
	v_max_f32_e64 v39, -v43, -v43
	v_mul_f32_e64 v43, |v43|, s16
	v_exp_f32_e32 v43, v43
	v_add_f32_e32 v28, 1.0, v28
	v_rcp_f32_e32 v28, v28
	v_max_f32_e32 v39, 0, v39
	v_add_f32_e32 v46, 1.0, v43
	v_add_f32_e32 v44, -1.0, v46
	v_sub_f32_e32 v45, v44, v46
	v_add_f32_e32 v45, 1.0, v45
	v_sub_f32_e32 v44, v43, v44
	v_add_f32_e32 v47, v44, v45
	v_frexp_mant_f32_e32 v44, v46
	v_cmp_gt_f32_e32 vcc, s17, v44
	v_cvt_f64_f32_e32 v[44:45], v46
	v_frexp_exp_i32_f64_e32 v44, v[44:45]
	v_subbrev_co_u32_e32 v44, vcc, 0, v44, vcc
	v_sub_u32_e32 v45, 0, v44
	v_ldexp_f32 v46, v46, v45
	v_ldexp_f32 v45, v47, v45
	v_add_f32_e32 v47, -1.0, v46
	v_add_f32_e32 v48, 1.0, v47
	v_sub_f32_e32 v48, v46, v48
	v_add_f32_e32 v48, v45, v48
	v_add_f32_e32 v49, v47, v48
	v_sub_f32_e32 v47, v49, v47
	v_sub_f32_e32 v47, v48, v47
	v_add_f32_e32 v48, 1.0, v46
	v_add_f32_e32 v50, -1.0, v48
	v_sub_f32_e32 v46, v46, v50
	v_add_f32_e32 v45, v45, v46
	v_add_f32_e32 v46, v48, v45
	v_sub_f32_e32 v48, v46, v48
	v_sub_f32_e32 v45, v45, v48
	v_rcp_f32_e32 v48, v46
	v_cvt_f32_i32_e32 v44, v44
	v_cmp_neq_f32_e32 vcc, s3, v43
	v_mul_f32_e32 v28, 0xc1000000, v28
	v_mul_f32_e32 v50, v49, v48
	v_mul_f32_e32 v51, v46, v50
	v_fma_f32 v66, v50, v46, -v51
	v_fmac_f32_e32 v66, v50, v45
	v_add_f32_e32 v67, v51, v66
	v_sub_f32_e32 v68, v49, v67
	v_sub_f32_e32 v49, v49, v68
	v_sub_f32_e32 v51, v67, v51
	v_sub_f32_e32 v49, v49, v67
	v_add_f32_e32 v47, v47, v49
	v_sub_f32_e32 v49, v51, v66
	v_add_f32_e32 v47, v49, v47
	v_add_f32_e32 v49, v68, v47
	v_mul_f32_e32 v51, v48, v49
	v_mul_f32_e32 v66, v46, v51
	v_fma_f32 v46, v51, v46, -v66
	v_fmac_f32_e32 v46, v51, v45
	v_sub_f32_e32 v45, v68, v49
	v_add_f32_e32 v45, v47, v45
	v_add_f32_e32 v47, v66, v46
	v_sub_f32_e32 v67, v49, v47
	v_sub_f32_e32 v49, v49, v67
	v_sub_f32_e32 v66, v47, v66
	v_sub_f32_e32 v47, v49, v47
	v_add_f32_e32 v45, v45, v47
	v_sub_f32_e32 v46, v66, v46
	v_add_f32_e32 v45, v46, v45
	v_add_f32_e32 v46, v50, v51
	v_add_f32_e32 v45, v67, v45
	v_sub_f32_e32 v47, v46, v50
	v_mul_f32_e32 v45, v48, v45
	v_sub_f32_e32 v47, v51, v47
	v_add_f32_e32 v45, v47, v45
	v_mul_f32_e32 v50, 0x3f317218, v44
	v_add_f32_e32 v47, v46, v45
	v_fma_f32 v51, v44, s19, -v50
	v_mul_f32_e32 v48, v47, v47
	v_fmac_f32_e32 v51, 0xb102e308, v44
	v_sub_f32_e32 v44, v47, v46
	v_fmamk_f32 v49, v48, 0x3e9b6dac, v170
	v_sub_f32_e32 v44, v45, v44
	v_add_f32_e32 v45, v50, v51
	v_fmaak_f32 v49, v48, v49, 0x3f2aaada
	v_sub_f32_e32 v46, v45, v50
	v_ldexp_f32 v50, v47, 1
	v_mul_f32_e32 v47, v47, v48
	v_mul_f32_e32 v47, v47, v49
	v_add_f32_e32 v48, v50, v47
	v_sub_f32_e32 v49, v48, v50
	v_ldexp_f32 v44, v44, 1
	v_sub_f32_e32 v47, v47, v49
	v_add_f32_e32 v44, v44, v47
	v_add_f32_e32 v47, v48, v44
	v_sub_f32_e32 v48, v47, v48
	v_sub_f32_e32 v44, v44, v48
	v_add_f32_e32 v48, v45, v47
	v_sub_f32_e32 v49, v48, v45
	v_sub_f32_e32 v50, v48, v49
	v_sub_f32_e32 v46, v51, v46
	v_sub_f32_e32 v45, v45, v50
	v_sub_f32_e32 v47, v47, v49
	v_add_f32_e32 v45, v47, v45
	v_add_f32_e32 v47, v46, v44
	v_sub_f32_e32 v49, v47, v46
	v_sub_f32_e32 v50, v47, v49
	v_sub_f32_e32 v46, v46, v50
	v_sub_f32_e32 v44, v44, v49
	v_add_f32_e32 v45, v47, v45
	v_add_f32_e32 v44, v44, v46
	v_add_f32_e32 v46, v48, v45
	v_sub_f32_e32 v47, v46, v48
	v_sub_f32_e32 v45, v45, v47
	v_add_f32_e32 v44, v44, v45
	v_add_f32_e32 v44, v46, v44
	v_cndmask_b32_e32 v44, v187, v44, vcc
	v_cmp_ngt_f32_e32 vcc, -1.0, v43
	s_waitcnt vmcnt(0)
; __device__ __forceinline__ float sigmoid_(float x) { return __builtin_amdgcn_rcpf(1.f + __expf(-x)); }
; __device__ __forceinline__ float softplus_(float x) { return fmaxf(x, 0.f) + log1pf(__expf(-fabsf(x))); }
; __device__ __forceinline__ unsigned f2bf(float f) { unsigned u = __builtin_bit_cast(unsigned, f); return (u + 0x7fffu + ((u >> 16) & 1u)) >> 16; }
; __device__ __forceinline__ void prep_phase(const Params& P, float* L, int l) {
;     ...
;             for (int jt = 0; jt < 4; ++jt) {
;                 const int j = jt * 16 + fr, c = h * 64 + j;
;                 const float ba1 = P.lru_ba[(size_t)(l * 2 + d) * 512 + c], bx1 = P.lru_bx[(size_t)(l * 2 + d) * 512 + c], sp = softplus_(-P.lru_lambda[(size_t)(l * 2 + d) * 512 + c]);
; #pragma unroll
;                 for (int jj = 0; jj < 4; ++jj) {
;                     const int t = tt * 16 + 4 * fq + jj, row = row0 + t;
;                     const float rg = sigmoid_(acc[0][jt][jj] + ba1), ig = sigmoid_(acc[1][jt][jj] + bx1);
;                     const float la = -8.f * rg * sp;
;                     const float a_ = __expf(la); LA[((size_t)d * MALL + row) * 512 + c] = a_;
;                     LB[((size_t)d * MALL + row) * 512 + c] = (bf16)f2bf(sqrtf(fmaxf(1.f - a_ * a_, 1e-12f)) * (ig * xs[t * 68 + j]));
;                 }
	v_add_f32_e32 v32, v32, v41
	v_mul_f32_e32 v32, 0xbfb8aa3b, v32
	v_cndmask_b32_e32 v44, v188, v44, vcc
	v_cmp_neq_f32_e32 vcc, -1.0, v43
	v_exp_f32_e32 v32, v32
	v_add_u32_e32 v66, 0xb400, v65
	v_cndmask_b32_e32 v44, v189, v44, vcc
	v_cmp_lt_f32_e64 vcc, |v43|, s20
	v_mul_f32_e32 v29, 0xbfb8aa3b, v29
	v_add_f32_e32 v32, 1.0, v32
	v_cndmask_b32_e32 v43, v44, v43, vcc
	v_add_f32_e32 v43, v39, v43
	v_mov_b32_e32 v108, v43
	v_mul_f32_e32 v28, v28, v43
	v_mul_f32_e32 v28, 0x3fb8aa3b, v28
	v_ashrrev_i32_e32 v39, 31, v38
	v_exp_f32_e32 v28, v28
	v_lshl_add_u64 v[38:39], s[86:87], 0, v[38:39]
	v_lshlrev_b64 v[38:39], 9, v[38:39]
	v_or_b32_e32 v44, v38, v2
	v_mov_b32_e32 v45, v39
	v_lshl_add_u64 v[46:47], v[44:45], 2, s[0:1]
	global_store_dword v[46:47], v28, off
	v_fma_f32 v28, -v28, v28, 1.0
	v_max_f32_e32 v28, 0x2b8cbccc, v28
	v_cmp_gt_f32_e32 vcc, s18, v28
	v_mul_f32_e32 v46, 0x4f800000, v28
	v_exp_f32_e32 v29, v29
	v_cndmask_b32_e32 v28, v28, v46, vcc
	v_sqrt_f32_e32 v46, v28
	v_rcp_f32_e32 v32, v32
	v_add_f32_e32 v29, 1.0, v29
	v_rcp_f32_e32 v29, v29
	v_add_u32_e32 v47, -1, v46
	v_fma_f32 v48, -v47, v46, v28
	v_cmp_ge_f32_e64 s[12:13], 0, v48
	v_add_u32_e32 v48, 1, v46
	v_mul_f32_e32 v29, 0xc1000000, v29
	v_cndmask_b32_e64 v47, v46, v47, s[12:13]
	v_fma_f32 v46, -v48, v46, v28
	v_cmp_lt_f32_e64 s[12:13], 0, v46
	v_lshl_add_u64 v[44:45], v[44:45], 1, s[4:5]
	v_mul_f32_e32 v29, v29, v43
	v_cndmask_b32_e64 v46, v47, v48, s[12:13]
	v_mul_f32_e32 v47, 0x37800000, v46
	v_cndmask_b32_e32 v46, v46, v47, vcc
	v_cmp_class_f32_e32 vcc, v28, v171
	v_mul_f32_e32 v29, 0x3fb8aa3b, v29
	v_exp_f32_e32 v48, v29
	v_cndmask_b32_e32 v28, v46, v28, vcc
	ds_read2_b32 v[46:47], v66 offset1:16
	v_add_f32_e32 v30, v30, v42
	v_mul_f32_e32 v30, 0xbfb8aa3b, v30
	v_exp_f32_e32 v30, v30
	v_add_f32_e32 v31, v31, v42
	s_waitcnt lgkmcnt(0)
	v_mul_f32_e32 v32, v46, v32
	v_mul_f32_e32 v28, v32, v28
	v_bfe_u32 v32, v28, 16, 1
	v_add3_u32 v28, v28, v32, s71
	v_add_f32_e32 v32, v33, v41
	v_mul_f32_e32 v32, 0xbfb8aa3b, v32
	v_exp_f32_e32 v32, v32
	global_store_short_d16_hi v[44:45], v28, off
	v_or_b32_e32 v28, s49, v56
	v_ashrrev_i32_e32 v29, 31, v28
	v_lshl_add_u64 v[28:29], s[86:87], 0, v[28:29]
	v_add_f32_e32 v32, 1.0, v32
	v_lshlrev_b64 v[28:29], 9, v[28:29]
	v_rcp_f32_e32 v46, v32
	v_or_b32_e32 v32, v28, v2
	v_mov_b32_e32 v33, v29
	v_lshl_add_u64 v[44:45], v[32:33], 2, s[0:1]
	global_store_dword v[44:45], v48, off
	v_fma_f32 v44, -v48, v48, 1.0
	v_max_f32_e32 v44, 0x2b8cbccc, v44
	v_cmp_gt_f32_e32 vcc, s18, v44
	v_mul_f32_e32 v45, 0x4f800000, v44
	v_lshl_add_u64 v[32:33], v[32:33], 1, s[4:5]
	v_cndmask_b32_e32 v44, v44, v45, vcc
	v_sqrt_f32_e32 v45, v44
	v_add_f32_e32 v30, 1.0, v30
	v_rcp_f32_e32 v30, v30
	v_mul_f32_e32 v31, 0xbfb8aa3b, v31
	v_add_u32_e32 v48, -1, v45
	v_fma_f32 v49, -v48, v45, v44
	v_cmp_ge_f32_e64 s[12:13], 0, v49
	v_add_u32_e32 v49, 1, v45
	v_mul_f32_e32 v30, 0xc1000000, v30
	v_cndmask_b32_e64 v48, v45, v48, s[12:13]
	v_fma_f32 v45, -v49, v45, v44
	v_cmp_lt_f32_e64 s[12:13], 0, v45
	v_mul_f32_e32 v30, v30, v43
	v_mul_f32_e32 v30, 0x3fb8aa3b, v30
	v_cndmask_b32_e64 v45, v48, v49, s[12:13]
	v_mul_f32_e32 v48, 0x37800000, v45
	v_cndmask_b32_e32 v45, v45, v48, vcc
	ds_read2_b32 v[48:49], v66 offset0:68 offset1:84
	v_cmp_class_f32_e32 vcc, v44, v171
	v_exp_f32_e32 v30, v30
	v_exp_f32_e32 v31, v31
	v_cndmask_b32_e32 v44, v45, v44, vcc
	s_waitcnt lgkmcnt(0)
	v_mul_f32_e32 v45, v46, v48
	v_mul_f32_e32 v44, v45, v44
	v_bfe_u32 v45, v44, 16, 1
	v_add3_u32 v44, v44, v45, s71
	global_store_short_d16_hi v[32:33], v44, off
	v_add_f32_e32 v33, v34, v41
	v_mul_f32_e32 v33, 0xbfb8aa3b, v33
	v_exp_f32_e32 v33, v33
	v_or_b32_e32 v32, s49, v57
	v_add_f32_e32 v31, 1.0, v31
	v_rcp_f32_e32 v31, v31
	v_add_f32_e32 v33, 1.0, v33
	v_rcp_f32_e32 v34, v33
	v_ashrrev_i32_e32 v33, 31, v32
	v_lshl_add_u64 v[32:33], s[86:87], 0, v[32:33]
	v_lshlrev_b64 v[32:33], 9, v[32:33]
	v_or_b32_e32 v50, v32, v2
	v_mov_b32_e32 v51, v33
	v_lshl_add_u64 v[44:45], v[50:51], 2, s[0:1]
	global_store_dword v[44:45], v30, off
	v_fma_f32 v30, -v30, v30, 1.0
	v_max_f32_e32 v30, 0x2b8cbccc, v30
	v_cmp_gt_f32_e32 vcc, s18, v30
	v_mul_f32_e32 v44, 0x4f800000, v30
	v_mul_f32_e32 v31, 0xc1000000, v31
	v_cndmask_b32_e32 v30, v30, v44, vcc
	v_sqrt_f32_e32 v44, v30
	v_mul_f32_e32 v31, v31, v43
	v_lshl_add_u64 v[50:51], v[50:51], 1, s[4:5]
	v_mul_f32_e32 v31, 0x3fb8aa3b, v31
	v_add_u32_e32 v45, -1, v44
	v_fma_f32 v46, -v45, v44, v30
	v_cmp_ge_f32_e64 s[12:13], 0, v46
	v_add_u32_e32 v46, 1, v44
	s_nop 0
	v_cndmask_b32_e64 v45, v44, v45, s[12:13]
	v_fma_f32 v44, -v46, v44, v30
	v_cmp_lt_f32_e64 s[12:13], 0, v44
	s_nop 1
	v_cndmask_b32_e64 v44, v45, v46, s[12:13]
	v_mul_f32_e32 v45, 0x37800000, v44
	v_cndmask_b32_e32 v44, v44, v45, vcc
	v_cmp_class_f32_e32 vcc, v30, v171
	s_nop 1
	v_cndmask_b32_e32 v30, v44, v30, vcc
	ds_read2_b32 v[44:45], v66 offset0:136 offset1:152
	s_waitcnt lgkmcnt(0)
	v_mul_f32_e32 v34, v34, v44
	v_mul_f32_e32 v30, v34, v30
	v_bfe_u32 v34, v30, 16, 1
	v_add3_u32 v30, v30, v34, s71
	v_add_f32_e32 v34, v35, v41
	v_mul_f32_e32 v34, 0xbfb8aa3b, v34
	v_exp_f32_e32 v34, v34
	global_store_short_d16_hi v[50:51], v30, off
	v_or_b32_e32 v30, s49, v58
	v_exp_f32_e32 v44, v31
	v_ashrrev_i32_e32 v31, 31, v30
	v_lshl_add_u64 v[30:31], s[86:87], 0, v[30:31]
	v_add_f32_e32 v34, 1.0, v34
	v_lshlrev_b64 v[30:31], 9, v[30:31]
	v_rcp_f32_e32 v41, v34
	v_or_b32_e32 v34, v30, v2
	v_mov_b32_e32 v35, v31
	v_fma_f32 v2, -v44, v44, 1.0
	v_lshl_add_u64 v[42:43], v[34:35], 2, s[0:1]
	v_max_f32_e32 v2, 0x2b8cbccc, v2
	global_store_dword v[42:43], v44, off
	v_cmp_gt_f32_e32 vcc, s18, v2
	v_mul_f32_e32 v42, 0x4f800000, v2
	ds_read2_b32 v[50:51], v66 offset0:204 offset1:220
	v_cndmask_b32_e32 v2, v2, v42, vcc
	v_sqrt_f32_e32 v42, v2
	v_lshl_add_u64 v[34:35], v[34:35], 1, s[4:5]
	s_waitcnt lgkmcnt(0)
; __device__ __forceinline__ float sigmoid_(float x) { return __builtin_amdgcn_rcpf(1.f + __expf(-x)); }
; __device__ __forceinline__ float softplus_(float x) { return fmaxf(x, 0.f) + log1pf(__expf(-fabsf(x))); }
; __device__ __forceinline__ unsigned f2bf(float f) { unsigned u = __builtin_bit_cast(unsigned, f); return (u + 0x7fffu + ((u >> 16) & 1u)) >> 16; }
; __device__ __forceinline__ void prep_phase(const Params& P, float* L, int l) {
;     ...
;             for (int jt = 0; jt < 4; ++jt) {
;                 const int j = jt * 16 + fr, c = h * 64 + j;
;                 const float ba1 = P.lru_ba[(size_t)(l * 2 + d) * 512 + c], bx1 = P.lru_bx[(size_t)(l * 2 + d) * 512 + c], sp = softplus_(-P.lru_lambda[(size_t)(l * 2 + d) * 512 + c]);
; #pragma unroll
;                 for (int jj = 0; jj < 4; ++jj) {
;                     const int t = tt * 16 + 4 * fq + jj, row = row0 + t;
;                     const float rg = sigmoid_(acc[0][jt][jj] + ba1), ig = sigmoid_(acc[1][jt][jj] + bx1);
;                     const float la = -8.f * rg * sp;
;                     const float a_ = __expf(la); LA[((size_t)d * MALL + row) * 512 + c] = a_;
;                     LB[((size_t)d * MALL + row) * 512 + c] = (bf16)f2bf(sqrtf(fmaxf(1.f - a_ * a_, 1e-12f)) * (ig * xs[t * 68 + j]));
;                 }
	v_mul_f32_e32 v41, v41, v50
	v_add_u32_e32 v43, -1, v42
	v_fma_f32 v44, -v43, v42, v2
	v_cmp_ge_f32_e64 s[12:13], 0, v44
	v_add_u32_e32 v44, 1, v42
	s_nop 0
	v_cndmask_b32_e64 v43, v42, v43, s[12:13]
	v_fma_f32 v42, -v44, v42, v2
	v_cmp_lt_f32_e64 s[12:13], 0, v42
	s_nop 1
	v_cndmask_b32_e64 v42, v43, v44, s[12:13]
	v_mul_f32_e32 v43, 0x37800000, v42
	v_cndmask_b32_e32 v42, v42, v43, vcc
	v_cmp_class_f32_e32 vcc, v2, v171
	v_or_b32_e32 v44, s58, v59
	s_nop 0
	v_cndmask_b32_e32 v2, v42, v2, vcc
	v_mul_f32_e32 v2, v41, v2
	v_bfe_u32 v41, v2, 16, 1
	v_add3_u32 v2, v2, v41, s71
	global_store_short_d16_hi v[34:35], v2, off
	v_add_u32_e32 v2, v40, v53
	v_lshl_add_u64 v[34:35], s[80:81], 0, v[2:3]
	v_lshlrev_b64 v[34:35], 2, v[34:35]
	v_lshl_add_u64 v[40:41], s[28:29], 0, v[34:35]
	v_lshl_add_u64 v[42:43], s[60:61], 0, v[34:35]
	v_lshl_add_u64 v[34:35], s[62:63], 0, v[34:35]
	global_load_dword v48, v[34:35], off offset:64
	global_load_dword v46, v[40:41], off offset:64
	global_load_dword v2, v[42:43], off offset:64
	s_waitcnt vmcnt(2)
	v_max_f32_e64 v50, -v48, -v48
	v_mul_f32_e64 v48, |v48|, s16
	v_exp_f32_e32 v48, v48
	s_waitcnt vmcnt(1)
	v_add_f32_e32 v20, v20, v46
	v_mul_f32_e32 v20, 0xbfb8aa3b, v20
	v_exp_f32_e32 v20, v20
	v_add_f32_e32 v67, 1.0, v48
	v_add_f32_e32 v68, -1.0, v67
	v_sub_f32_e32 v69, v68, v67
	v_add_f32_e32 v69, 1.0, v69
	v_sub_f32_e32 v68, v48, v68
	v_add_f32_e32 v70, v68, v69
	v_frexp_mant_f32_e32 v68, v67
	v_cmp_gt_f32_e32 vcc, s17, v68
	v_cvt_f64_f32_e32 v[68:69], v67
	v_frexp_exp_i32_f64_e32 v68, v[68:69]
	v_subbrev_co_u32_e32 v68, vcc, 0, v68, vcc
	v_sub_u32_e32 v69, 0, v68
	v_ldexp_f32 v67, v67, v69
	v_ldexp_f32 v69, v70, v69
	v_add_f32_e32 v70, -1.0, v67
	v_add_f32_e32 v71, 1.0, v70
	v_sub_f32_e32 v71, v67, v71
	v_add_f32_e32 v71, v69, v71
	v_add_f32_e32 v72, v70, v71
	v_sub_f32_e32 v70, v72, v70
	v_sub_f32_e32 v70, v71, v70
	v_add_f32_e32 v71, 1.0, v67
	v_add_f32_e32 v73, -1.0, v71
	v_sub_f32_e32 v67, v67, v73
	v_add_f32_e32 v67, v69, v67
	v_add_f32_e32 v69, v71, v67
	v_sub_f32_e32 v71, v69, v71
	v_sub_f32_e32 v67, v67, v71
	v_rcp_f32_e32 v71, v69
	v_cvt_f32_i32_e32 v68, v68
	v_cmp_neq_f32_e32 vcc, s3, v48
	v_add_f32_e32 v20, 1.0, v20
	v_mul_f32_e32 v73, v72, v71
	v_mul_f32_e32 v74, v69, v73
	v_fma_f32 v75, v73, v69, -v74
	v_fmac_f32_e32 v75, v73, v67
	v_add_f32_e32 v76, v74, v75
	v_sub_f32_e32 v77, v72, v76
	v_sub_f32_e32 v72, v72, v77
	v_sub_f32_e32 v74, v76, v74
	v_sub_f32_e32 v72, v72, v76
	v_add_f32_e32 v70, v70, v72
	v_sub_f32_e32 v72, v74, v75
	v_add_f32_e32 v70, v72, v70
	v_add_f32_e32 v72, v77, v70
	v_mul_f32_e32 v74, v71, v72
	v_mul_f32_e32 v75, v69, v74
	v_fma_f32 v69, v74, v69, -v75
	v_fmac_f32_e32 v69, v74, v67
	v_sub_f32_e32 v67, v77, v72
	v_add_f32_e32 v67, v70, v67
	v_add_f32_e32 v70, v75, v69
	v_sub_f32_e32 v76, v72, v70
	v_sub_f32_e32 v72, v72, v76
	v_sub_f32_e32 v75, v70, v75
	v_sub_f32_e32 v70, v72, v70
	v_add_f32_e32 v67, v67, v70
	v_sub_f32_e32 v69, v75, v69
	v_add_f32_e32 v67, v69, v67
	v_add_f32_e32 v69, v73, v74
	v_add_f32_e32 v67, v76, v67
	v_sub_f32_e32 v70, v69, v73
	v_mul_f32_e32 v67, v71, v67
	v_sub_f32_e32 v70, v74, v70
	v_add_f32_e32 v67, v70, v67
	v_mul_f32_e32 v73, 0x3f317218, v68
	v_add_f32_e32 v70, v69, v67
	v_fma_f32 v74, v68, s19, -v73
	v_mul_f32_e32 v71, v70, v70
	v_fmac_f32_e32 v74, 0xb102e308, v68
	v_sub_f32_e32 v68, v70, v69
	v_fmamk_f32 v72, v71, 0x3e9b6dac, v170
	v_sub_f32_e32 v67, v67, v68
	v_add_f32_e32 v68, v73, v74
	v_fmaak_f32 v72, v71, v72, 0x3f2aaada
	v_sub_f32_e32 v69, v68, v73
	v_ldexp_f32 v73, v70, 1
	v_mul_f32_e32 v70, v70, v71
	v_mul_f32_e32 v70, v70, v72
	v_add_f32_e32 v71, v73, v70
	v_sub_f32_e32 v72, v71, v73
	v_ldexp_f32 v67, v67, 1
	v_sub_f32_e32 v70, v70, v72
	v_add_f32_e32 v67, v67, v70
	v_add_f32_e32 v70, v71, v67
	v_sub_f32_e32 v71, v70, v71
	v_sub_f32_e32 v67, v67, v71
	v_add_f32_e32 v71, v68, v70
	v_sub_f32_e32 v72, v71, v68
	v_sub_f32_e32 v73, v71, v72
	v_sub_f32_e32 v69, v74, v69
	v_sub_f32_e32 v68, v68, v73
	v_sub_f32_e32 v70, v70, v72
	v_add_f32_e32 v68, v70, v68
	v_add_f32_e32 v70, v69, v67
	v_sub_f32_e32 v72, v70, v69
	v_sub_f32_e32 v73, v70, v72
	v_sub_f32_e32 v69, v69, v73
	v_sub_f32_e32 v67, v67, v72
	v_add_f32_e32 v68, v70, v68
	v_add_f32_e32 v67, v67, v69
	v_add_f32_e32 v69, v71, v68
	v_sub_f32_e32 v70, v69, v71
	v_sub_f32_e32 v68, v68, v70
	v_add_f32_e32 v67, v67, v68
	v_add_f32_e32 v67, v69, v67
	v_cndmask_b32_e32 v67, v187, v67, vcc
	v_cmp_ngt_f32_e32 vcc, -1.0, v48
	v_rcp_f32_e32 v20, v20
	v_max_f32_e32 v50, 0, v50
	v_cndmask_b32_e32 v67, v188, v67, vcc
	v_cmp_neq_f32_e32 vcc, -1.0, v48
	v_mul_f32_e32 v20, 0xc1000000, v20
	v_or_b32_e32 v68, v38, v44
	v_cndmask_b32_e32 v67, v189, v67, vcc
	v_cmp_lt_f32_e64 vcc, |v48|, s20
	v_mov_b32_e32 v69, v39
	v_lshl_add_u64 v[70:71], v[68:69], 2, s[0:1]
	v_cndmask_b32_e32 v48, v67, v48, vcc
	v_add_f32_e32 v48, v50, v48
	v_mov_b32_e32 v109, v48
	v_mul_f32_e32 v20, v20, v48
	v_mul_f32_e32 v20, 0x3fb8aa3b, v20
	v_exp_f32_e32 v20, v20
	s_waitcnt vmcnt(0)
; __device__ __forceinline__ float sigmoid_(float x) { return __builtin_amdgcn_rcpf(1.f + __expf(-x)); }
; __device__ __forceinline__ float softplus_(float x) { return fmaxf(x, 0.f) + log1pf(__expf(-fabsf(x))); }
; __device__ __forceinline__ unsigned f2bf(float f) { unsigned u = __builtin_bit_cast(unsigned, f); return (u + 0x7fffu + ((u >> 16) & 1u)) >> 16; }
; __device__ __forceinline__ void prep_phase(const Params& P, float* L, int l) {
;     ...
;             for (int jt = 0; jt < 4; ++jt) {
;                 const int j = jt * 16 + fr, c = h * 64 + j;
;                 const float ba1 = P.lru_ba[(size_t)(l * 2 + d) * 512 + c], bx1 = P.lru_bx[(size_t)(l * 2 + d) * 512 + c], sp = softplus_(-P.lru_lambda[(size_t)(l * 2 + d) * 512 + c]);
; #pragma unroll
;                 for (int jj = 0; jj < 4; ++jj) {
;                     const int t = tt * 16 + 4 * fq + jj, row = row0 + t;
;                     const float rg = sigmoid_(acc[0][jt][jj] + ba1), ig = sigmoid_(acc[1][jt][jj] + bx1);
;                     const float la = -8.f * rg * sp;
;                     const float a_ = __expf(la); LA[((size_t)d * MALL + row) * 512 + c] = a_;
;                     LB[((size_t)d * MALL + row) * 512 + c] = (bf16)f2bf(sqrtf(fmaxf(1.f - a_ * a_, 1e-12f)) * (ig * xs[t * 68 + j]));
;                 }
	v_add_f32_e32 v24, v24, v2
	v_mul_f32_e32 v24, 0xbfb8aa3b, v24
	v_exp_f32_e32 v24, v24
	global_store_dword v[70:71], v20, off
	v_fma_f32 v20, -v20, v20, 1.0
	v_max_f32_e32 v20, 0x2b8cbccc, v20
	v_cmp_gt_f32_e32 vcc, s18, v20
	v_mul_f32_e32 v50, 0x4f800000, v20
	v_add_f32_e32 v24, 1.0, v24
	v_cndmask_b32_e32 v20, v20, v50, vcc
	v_sqrt_f32_e32 v50, v20
	v_rcp_f32_e32 v24, v24
	v_lshl_add_u64 v[68:69], v[68:69], 1, s[4:5]
	v_add_u32_e32 v67, -1, v50
	v_fma_f32 v70, -v67, v50, v20
	v_cmp_ge_f32_e64 s[12:13], 0, v70
	v_add_u32_e32 v70, 1, v50
	v_mul_f32_e32 v24, v47, v24
	v_cndmask_b32_e64 v67, v50, v67, s[12:13]
	v_fma_f32 v50, -v70, v50, v20
	v_cmp_lt_f32_e64 s[12:13], 0, v50
	s_nop 1
	v_cndmask_b32_e64 v50, v67, v70, s[12:13]
	v_mul_f32_e32 v67, 0x37800000, v50
	v_cndmask_b32_e32 v50, v50, v67, vcc
	v_cmp_class_f32_e32 vcc, v20, v171
	s_nop 1
	v_cndmask_b32_e32 v20, v50, v20, vcc
	v_mul_f32_e32 v20, v24, v20
	v_bfe_u32 v24, v20, 16, 1
	v_add3_u32 v20, v20, v24, s71
	global_store_short_d16_hi v[68:69], v20, off
	v_add_f32_e32 v20, v21, v46
	v_mul_f32_e32 v20, 0xbfb8aa3b, v20
	v_exp_f32_e32 v20, v20
	v_add_f32_e32 v21, v25, v2
	v_mul_f32_e32 v21, 0xbfb8aa3b, v21
	v_exp_f32_e32 v21, v21
	v_add_f32_e32 v20, 1.0, v20
	v_rcp_f32_e32 v20, v20
	v_add_f32_e32 v21, 1.0, v21
	v_rcp_f32_e32 v47, v21
	v_mul_f32_e32 v20, 0xc1000000, v20
	v_mul_f32_e32 v20, v20, v48
	v_mul_f32_e32 v20, 0x3fb8aa3b, v20
	v_exp_f32_e32 v50, v20
	v_or_b32_e32 v20, v28, v44
	v_mov_b32_e32 v21, v29
	v_lshl_add_u64 v[24:25], v[20:21], 2, s[0:1]
	global_store_dword v[24:25], v50, off
	v_fma_f32 v24, -v50, v50, 1.0
	v_max_f32_e32 v24, 0x2b8cbccc, v24
	v_cmp_gt_f32_e32 vcc, s18, v24
	v_mul_f32_e32 v25, 0x4f800000, v24
	v_lshl_add_u64 v[20:21], v[20:21], 1, s[4:5]
	v_cndmask_b32_e32 v24, v24, v25, vcc
	v_sqrt_f32_e32 v25, v24
	s_nop 0
	v_add_u32_e32 v50, -1, v25
	v_fma_f32 v67, -v50, v25, v24
	v_cmp_ge_f32_e64 s[12:13], 0, v67
	v_add_u32_e32 v67, 1, v25
	s_nop 0
	v_cndmask_b32_e64 v50, v25, v50, s[12:13]
	v_fma_f32 v25, -v67, v25, v24
	v_cmp_lt_f32_e64 s[12:13], 0, v25
	s_nop 1
	v_cndmask_b32_e64 v25, v50, v67, s[12:13]
	v_mul_f32_e32 v50, 0x37800000, v25
	v_cndmask_b32_e32 v25, v25, v50, vcc
	v_cmp_class_f32_e32 vcc, v24, v171
	s_nop 1
	v_cndmask_b32_e32 v24, v25, v24, vcc
	v_mul_f32_e32 v25, v47, v49
	v_mul_f32_e32 v24, v25, v24
	v_bfe_u32 v25, v24, 16, 1
	v_add3_u32 v24, v24, v25, s71
	global_store_short_d16_hi v[20:21], v24, off
	v_add_f32_e32 v20, v22, v46
	v_mul_f32_e32 v20, 0xbfb8aa3b, v20
	v_exp_f32_e32 v20, v20
	v_add_f32_e32 v21, v26, v2
	v_mul_f32_e32 v21, 0xbfb8aa3b, v21
	v_exp_f32_e32 v21, v21
	v_add_f32_e32 v20, 1.0, v20
	v_rcp_f32_e32 v20, v20
	v_add_f32_e32 v2, v27, v2
	v_add_f32_e32 v21, 1.0, v21
	v_rcp_f32_e32 v22, v21
	v_mul_f32_e32 v20, 0xc1000000, v20
	v_mul_f32_e32 v20, v20, v48
	v_mul_f32_e32 v20, 0x3fb8aa3b, v20
	v_exp_f32_e32 v26, v20
	v_or_b32_e32 v20, v32, v44
	v_mov_b32_e32 v21, v33
	v_lshl_add_u64 v[24:25], v[20:21], 2, s[0:1]
	global_store_dword v[24:25], v26, off
	v_fma_f32 v24, -v26, v26, 1.0
	v_max_f32_e32 v24, 0x2b8cbccc, v24
	v_cmp_gt_f32_e32 vcc, s18, v24
	v_mul_f32_e32 v25, 0x4f800000, v24
	v_mul_f32_e32 v22, v22, v45
	v_cndmask_b32_e32 v24, v24, v25, vcc
	v_sqrt_f32_e32 v25, v24
	v_lshl_add_u64 v[20:21], v[20:21], 1, s[4:5]
	v_mul_f32_e32 v2, 0xbfb8aa3b, v2
	v_exp_f32_e32 v2, v2
	v_add_u32_e32 v26, -1, v25
	v_fma_f32 v47, -v26, v25, v24
	v_cmp_ge_f32_e64 s[12:13], 0, v47
	v_add_u32_e32 v47, 1, v25
	v_add_f32_e32 v2, 1.0, v2
	v_cndmask_b32_e64 v26, v25, v26, s[12:13]
	v_fma_f32 v25, -v47, v25, v24
	v_cmp_lt_f32_e64 s[12:13], 0, v25
	v_rcp_f32_e32 v2, v2
	s_nop 0
	v_cndmask_b32_e64 v25, v26, v47, s[12:13]
	v_mul_f32_e32 v26, 0x37800000, v25
	v_cndmask_b32_e32 v25, v25, v26, vcc
	v_cmp_class_f32_e32 vcc, v24, v171
	v_mul_f32_e32 v2, v2, v51
	s_nop 0
	v_cndmask_b32_e32 v24, v25, v24, vcc
	v_mul_f32_e32 v22, v22, v24
	v_bfe_u32 v24, v22, 16, 1
	v_add3_u32 v22, v22, v24, s71
	global_store_short_d16_hi v[20:21], v22, off
	v_add_f32_e32 v20, v23, v46
	v_mul_f32_e32 v20, 0xbfb8aa3b, v20
	v_exp_f32_e32 v20, v20
	v_mov_b32_e32 v21, v31
	v_add_f32_e32 v20, 1.0, v20
	v_rcp_f32_e32 v20, v20
	s_nop 0
	v_mul_f32_e32 v20, 0xc1000000, v20
	v_mul_f32_e32 v20, v20, v48
	v_mul_f32_e32 v20, 0x3fb8aa3b, v20
	v_exp_f32_e32 v24, v20
	v_or_b32_e32 v20, v30, v44
	v_lshl_add_u64 v[22:23], v[20:21], 2, s[0:1]
	v_lshl_add_u64 v[20:21], v[20:21], 1, s[4:5]
	global_store_dword v[22:23], v24, off
	v_fma_f32 v22, -v24, v24, 1.0
	v_max_f32_e32 v22, 0x2b8cbccc, v22
	v_cmp_gt_f32_e32 vcc, s18, v22
	v_mul_f32_e32 v23, 0x4f800000, v22
	s_nop 0
	v_cndmask_b32_e32 v22, v22, v23, vcc
	v_sqrt_f32_e32 v23, v22
	s_nop 0
	v_add_u32_e32 v24, -1, v23
	v_fma_f32 v25, -v24, v23, v22
	v_cmp_ge_f32_e64 s[12:13], 0, v25
	v_add_u32_e32 v25, 1, v23
	s_nop 0
	v_cndmask_b32_e64 v24, v23, v24, s[12:13]
	v_fma_f32 v23, -v25, v23, v22
	v_cmp_lt_f32_e64 s[12:13], 0, v23
	s_nop 1
	v_cndmask_b32_e64 v23, v24, v25, s[12:13]
	v_mul_f32_e32 v24, 0x37800000, v23
	v_cndmask_b32_e32 v23, v23, v24, vcc
	v_cmp_class_f32_e32 vcc, v22, v171
	s_nop 1
	v_cndmask_b32_e32 v22, v23, v22, vcc
	v_mul_f32_e32 v2, v2, v22
	v_bfe_u32 v22, v2, 16, 1
	v_add3_u32 v2, v2, v22, s71
	global_store_short_d16_hi v[20:21], v2, off
	global_load_dword v23, v[40:41], off offset:128
	global_load_dword v22, v[42:43], off offset:128
	s_nop 0
	global_load_dword v20, v[34:35], off offset:128
	v_or_b32_e32 v2, s58, v60
	s_waitcnt vmcnt(2)
	v_add_f32_e32 v12, v12, v23
	v_mul_f32_e32 v12, 0xbfb8aa3b, v12
	s_waitcnt vmcnt(0)
; __device__ __forceinline__ float sigmoid_(float x) { return __builtin_amdgcn_rcpf(1.f + __expf(-x)); }
; __device__ __forceinline__ float softplus_(float x) { return fmaxf(x, 0.f) + log1pf(__expf(-fabsf(x))); }
; __device__ __forceinline__ unsigned f2bf(float f) { unsigned u = __builtin_bit_cast(unsigned, f); return (u + 0x7fffu + ((u >> 16) & 1u)) >> 16; }
; __device__ __forceinline__ void prep_phase(const Params& P, float* L, int l) {
;     ...
;             for (int jt = 0; jt < 4; ++jt) {
;                 const int j = jt * 16 + fr, c = h * 64 + j;
;                 const float ba1 = P.lru_ba[(size_t)(l * 2 + d) * 512 + c], bx1 = P.lru_bx[(size_t)(l * 2 + d) * 512 + c], sp = softplus_(-P.lru_lambda[(size_t)(l * 2 + d) * 512 + c]);
; #pragma unroll
;                 for (int jj = 0; jj < 4; ++jj) {
;                     const int t = tt * 16 + 4 * fq + jj, row = row0 + t;
;                     const float rg = sigmoid_(acc[0][jt][jj] + ba1), ig = sigmoid_(acc[1][jt][jj] + bx1);
;                     const float la = -8.f * rg * sp;
;                     const float a_ = __expf(la); LA[((size_t)d * MALL + row) * 512 + c] = a_;
;                     LB[((size_t)d * MALL + row) * 512 + c] = (bf16)f2bf(sqrtf(fmaxf(1.f - a_ * a_, 1e-12f)) * (ig * xs[t * 68 + j]));
;                 }
	v_max_f32_e64 v21, -v20, -v20
	v_mul_f32_e64 v20, |v20|, s16
	v_exp_f32_e32 v25, v20
	v_max_f32_e32 v24, 0, v21
	v_exp_f32_e32 v12, v12
	v_add_f32_e32 v16, v16, v22
	v_add_f32_e32 v26, 1.0, v25
	v_add_f32_e32 v20, -1.0, v26
	v_sub_f32_e32 v21, v20, v26
	v_add_f32_e32 v21, 1.0, v21
	v_sub_f32_e32 v20, v25, v20
	v_add_f32_e32 v27, v20, v21
	v_frexp_mant_f32_e32 v20, v26
	v_cmp_gt_f32_e32 vcc, s17, v20
	v_cvt_f64_f32_e32 v[20:21], v26
	v_frexp_exp_i32_f64_e32 v20, v[20:21]
	v_subbrev_co_u32_e32 v20, vcc, 0, v20, vcc
	v_sub_u32_e32 v21, 0, v20
	v_ldexp_f32 v26, v26, v21
	v_ldexp_f32 v21, v27, v21
	v_add_f32_e32 v27, -1.0, v26
	v_add_f32_e32 v44, 1.0, v27
	v_sub_f32_e32 v44, v26, v44
	v_add_f32_e32 v44, v21, v44
	v_add_f32_e32 v45, v27, v44
	v_sub_f32_e32 v27, v45, v27
	v_sub_f32_e32 v27, v44, v27
	v_add_f32_e32 v44, 1.0, v26
	v_add_f32_e32 v46, -1.0, v44
	v_sub_f32_e32 v26, v26, v46
	v_add_f32_e32 v21, v21, v26
	v_add_f32_e32 v26, v44, v21
	v_sub_f32_e32 v44, v26, v44
	v_sub_f32_e32 v21, v21, v44
	v_rcp_f32_e32 v44, v26
	v_cvt_f32_i32_e32 v20, v20
	v_cmp_neq_f32_e32 vcc, s3, v25
	v_add_f32_e32 v12, 1.0, v12
	v_mul_f32_e32 v46, v45, v44
	v_mul_f32_e32 v47, v26, v46
	v_fma_f32 v48, v46, v26, -v47
	v_fmac_f32_e32 v48, v46, v21
	v_add_f32_e32 v49, v47, v48
	v_sub_f32_e32 v50, v45, v49
	v_sub_f32_e32 v45, v45, v50
	v_sub_f32_e32 v47, v49, v47
	v_sub_f32_e32 v45, v45, v49
	v_add_f32_e32 v27, v27, v45
	v_sub_f32_e32 v45, v47, v48
	v_add_f32_e32 v27, v45, v27
	v_add_f32_e32 v45, v50, v27
	v_mul_f32_e32 v47, v44, v45
	v_mul_f32_e32 v48, v26, v47
	v_fma_f32 v26, v47, v26, -v48
	v_fmac_f32_e32 v26, v47, v21
	v_sub_f32_e32 v21, v50, v45
	v_add_f32_e32 v21, v27, v21
	v_add_f32_e32 v27, v48, v26
	v_sub_f32_e32 v49, v45, v27
	v_sub_f32_e32 v45, v45, v49
	v_sub_f32_e32 v48, v27, v48
	v_sub_f32_e32 v27, v45, v27
	v_add_f32_e32 v21, v21, v27
	v_sub_f32_e32 v26, v48, v26
	v_add_f32_e32 v21, v26, v21
	v_add_f32_e32 v26, v46, v47
	v_add_f32_e32 v21, v49, v21
	v_sub_f32_e32 v27, v26, v46
	v_mul_f32_e32 v21, v44, v21
	v_sub_f32_e32 v27, v47, v27
	v_add_f32_e32 v21, v27, v21
	v_mul_f32_e32 v46, 0x3f317218, v20
	v_add_f32_e32 v27, v26, v21
	v_fma_f32 v47, v20, s19, -v46
	v_mul_f32_e32 v44, v27, v27
	v_fmac_f32_e32 v47, 0xb102e308, v20
	v_sub_f32_e32 v20, v27, v26
	v_fmamk_f32 v45, v44, 0x3e9b6dac, v170
	v_sub_f32_e32 v20, v21, v20
	v_add_f32_e32 v21, v46, v47
	v_fmaak_f32 v45, v44, v45, 0x3f2aaada
	v_sub_f32_e32 v26, v21, v46
	v_ldexp_f32 v46, v27, 1
	v_mul_f32_e32 v27, v27, v44
	v_mul_f32_e32 v27, v27, v45
	v_add_f32_e32 v44, v46, v27
	v_sub_f32_e32 v45, v44, v46
	v_ldexp_f32 v20, v20, 1
	v_sub_f32_e32 v27, v27, v45
	v_add_f32_e32 v20, v20, v27
	v_add_f32_e32 v27, v44, v20
	v_sub_f32_e32 v44, v27, v44
	v_sub_f32_e32 v20, v20, v44
	v_add_f32_e32 v44, v21, v27
	v_sub_f32_e32 v45, v44, v21
	v_sub_f32_e32 v46, v44, v45
	v_sub_f32_e32 v26, v47, v26
	v_sub_f32_e32 v21, v21, v46
	v_sub_f32_e32 v27, v27, v45
	v_add_f32_e32 v21, v27, v21
	v_add_f32_e32 v27, v26, v20
	v_sub_f32_e32 v45, v27, v26
	v_sub_f32_e32 v46, v27, v45
	v_sub_f32_e32 v26, v26, v46
	v_sub_f32_e32 v20, v20, v45
	v_add_f32_e32 v21, v27, v21
	v_add_f32_e32 v20, v20, v26
	v_add_f32_e32 v26, v44, v21
	v_sub_f32_e32 v27, v26, v44
	v_sub_f32_e32 v21, v21, v27
	v_add_f32_e32 v20, v20, v21
	v_add_f32_e32 v20, v26, v20
	v_cndmask_b32_e32 v20, v187, v20, vcc
	v_cmp_ngt_f32_e32 vcc, -1.0, v25
	v_rcp_f32_e32 v12, v12
	v_or_b32_e32 v26, v38, v2
	v_cndmask_b32_e32 v20, v188, v20, vcc
	v_cmp_neq_f32_e32 vcc, -1.0, v25
	v_mul_f32_e32 v12, 0xc1000000, v12
	v_mov_b32_e32 v27, v39
	v_cndmask_b32_e32 v20, v189, v20, vcc
	v_cmp_lt_f32_e64 vcc, |v25|, s20
	v_mul_f32_e32 v16, 0xbfb8aa3b, v16
	v_exp_f32_e32 v16, v16
	v_cndmask_b32_e32 v20, v20, v25, vcc
	v_add_f32_e32 v24, v24, v20
	v_mov_b32_e32 v110, v24
	v_mul_f32_e32 v12, v12, v24
	v_mul_f32_e32 v12, 0x3fb8aa3b, v12
	v_exp_f32_e32 v12, v12
	v_lshl_add_u64 v[20:21], v[26:27], 2, s[0:1]
	v_add_f32_e32 v16, 1.0, v16
	v_rcp_f32_e32 v16, v16
	global_store_dword v[20:21], v12, off
	v_fma_f32 v12, -v12, v12, 1.0
	v_max_f32_e32 v12, 0x2b8cbccc, v12
	v_cmp_gt_f32_e32 vcc, s18, v12
	v_mul_f32_e32 v20, 0x4f800000, v12
	v_lshl_add_u64 v[26:27], v[26:27], 1, s[4:5]
	v_cndmask_b32_e32 v12, v12, v20, vcc
	v_sqrt_f32_e32 v20, v12
	s_nop 0
	v_add_u32_e32 v21, -1, v20
	v_fma_f32 v25, -v21, v20, v12
	v_cmp_ge_f32_e64 s[12:13], 0, v25
	v_add_u32_e32 v25, 1, v20
	s_nop 0
	v_cndmask_b32_e64 v21, v20, v21, s[12:13]
	v_fma_f32 v20, -v25, v20, v12
	v_cmp_lt_f32_e64 s[12:13], 0, v20
	s_nop 1
	v_cndmask_b32_e64 v20, v21, v25, s[12:13]
	v_mul_f32_e32 v21, 0x37800000, v20
	v_cndmask_b32_e32 v20, v20, v21, vcc
	v_cmp_class_f32_e32 vcc, v12, v171
	s_nop 1
	v_cndmask_b32_e32 v12, v20, v12, vcc
	ds_read2_b32 v[20:21], v66 offset0:32 offset1:48
	s_waitcnt lgkmcnt(0)
	v_mul_f32_e32 v16, v20, v16
	v_mul_f32_e32 v12, v16, v12
	v_bfe_u32 v16, v12, 16, 1
	v_add3_u32 v12, v12, v16, s71
	global_store_short_d16_hi v[26:27], v12, off
	v_add_f32_e32 v12, v13, v23
	v_mul_f32_e32 v12, 0xbfb8aa3b, v12
	v_exp_f32_e32 v12, v12
	v_add_f32_e32 v13, v17, v22
	v_mul_f32_e32 v13, 0xbfb8aa3b, v13
	v_exp_f32_e32 v13, v13
	v_add_f32_e32 v12, 1.0, v12
	v_rcp_f32_e32 v12, v12
	v_or_b32_e32 v16, v28, v2
	v_add_f32_e32 v13, 1.0, v13
	v_mov_b32_e32 v17, v29
	v_mul_f32_e32 v12, 0xc1000000, v12
	v_mul_f32_e32 v12, v12, v24
	v_mul_f32_e32 v12, 0x3fb8aa3b, v12
	v_exp_f32_e32 v25, v12
	v_rcp_f32_e32 v20, v13
	v_lshl_add_u64 v[12:13], v[16:17], 2, s[0:1]
	v_lshl_add_u64 v[16:17], v[16:17], 1, s[4:5]
	global_store_dword v[12:13], v25, off
	v_fma_f32 v12, -v25, v25, 1.0
	v_max_f32_e32 v12, 0x2b8cbccc, v12
	v_cmp_gt_f32_e32 vcc, s18, v12
	v_mul_f32_e32 v13, 0x4f800000, v12
	v_mov_b32_e32 v27, v33
	v_cndmask_b32_e32 v12, v12, v13, vcc
	v_sqrt_f32_e32 v13, v12
	s_nop 0
	v_add_u32_e32 v25, -1, v13
	v_fma_f32 v26, -v25, v13, v12
	v_cmp_ge_f32_e64 s[12:13], 0, v26
	v_add_u32_e32 v26, 1, v13
	s_nop 0
	v_cndmask_b32_e64 v25, v13, v25, s[12:13]
	v_fma_f32 v13, -v26, v13, v12
	v_cmp_lt_f32_e64 s[12:13], 0, v13
	s_nop 1
	v_cndmask_b32_e64 v13, v25, v26, s[12:13]
	v_mul_f32_e32 v25, 0x37800000, v13
	v_cndmask_b32_e32 v13, v13, v25, vcc
	v_cmp_class_f32_e32 vcc, v12, v171
	v_or_b32_e32 v26, v32, v2
	s_nop 0
	v_cndmask_b32_e32 v25, v13, v12, vcc
	ds_read2_b32 v[12:13], v66 offset0:100 offset1:116
	s_waitcnt lgkmcnt(0)
; __device__ __forceinline__ float sigmoid_(float x) { return __builtin_amdgcn_rcpf(1.f + __expf(-x)); }
; __device__ __forceinline__ float softplus_(float x) { return fmaxf(x, 0.f) + log1pf(__expf(-fabsf(x))); }
; __device__ __forceinline__ unsigned f2bf(float f) { unsigned u = __builtin_bit_cast(unsigned, f); return (u + 0x7fffu + ((u >> 16) & 1u)) >> 16; }
; __device__ __forceinline__ void prep_phase(const Params& P, float* L, int l) {
;     ...
;             for (int jt = 0; jt < 4; ++jt) {
;                 const int j = jt * 16 + fr, c = h * 64 + j;
;                 const float ba1 = P.lru_ba[(size_t)(l * 2 + d) * 512 + c], bx1 = P.lru_bx[(size_t)(l * 2 + d) * 512 + c], sp = softplus_(-P.lru_lambda[(size_t)(l * 2 + d) * 512 + c]);
; #pragma unroll
;                 for (int jj = 0; jj < 4; ++jj) {
;                     const int t = tt * 16 + 4 * fq + jj, row = row0 + t;
;                     const float rg = sigmoid_(acc[0][jt][jj] + ba1), ig = sigmoid_(acc[1][jt][jj] + bx1);
;                     const float la = -8.f * rg * sp;
;                     const float a_ = __expf(la); LA[((size_t)d * MALL + row) * 512 + c] = a_;
;                     LB[((size_t)d * MALL + row) * 512 + c] = (bf16)f2bf(sqrtf(fmaxf(1.f - a_ * a_, 1e-12f)) * (ig * xs[t * 68 + j]));
;                 }
	v_mul_f32_e32 v12, v20, v12
	v_mul_f32_e32 v12, v12, v25
	v_bfe_u32 v20, v12, 16, 1
	v_add3_u32 v12, v12, v20, s71
	global_store_short_d16_hi v[16:17], v12, off
	v_add_f32_e32 v12, v14, v23
	v_mul_f32_e32 v12, 0xbfb8aa3b, v12
	v_exp_f32_e32 v12, v12
	v_lshl_add_u64 v[16:17], v[26:27], 2, s[0:1]
	v_add_f32_e32 v14, v18, v22
	v_mul_f32_e32 v14, 0xbfb8aa3b, v14
	v_add_f32_e32 v12, 1.0, v12
	v_rcp_f32_e32 v12, v12
	v_exp_f32_e32 v14, v14
	v_lshl_add_u64 v[26:27], v[26:27], 1, s[4:5]
	v_mul_f32_e32 v12, 0xc1000000, v12
	v_mul_f32_e32 v12, v12, v24
	v_mul_f32_e32 v12, 0x3fb8aa3b, v12
	v_exp_f32_e32 v12, v12
	v_add_f32_e32 v14, 1.0, v14
	v_rcp_f32_e32 v14, v14
	global_store_dword v[16:17], v12, off
	v_fma_f32 v12, -v12, v12, 1.0
	v_max_f32_e32 v12, 0x2b8cbccc, v12
	v_cmp_gt_f32_e32 vcc, s18, v12
	v_mul_f32_e32 v16, 0x4f800000, v12
	s_nop 0
	v_cndmask_b32_e32 v12, v12, v16, vcc
	v_sqrt_f32_e32 v16, v12
	s_nop 0
	v_add_u32_e32 v17, -1, v16
	v_fma_f32 v18, -v17, v16, v12
	v_cmp_ge_f32_e64 s[12:13], 0, v18
	v_add_u32_e32 v18, 1, v16
	s_nop 0
	v_cndmask_b32_e64 v17, v16, v17, s[12:13]
	v_fma_f32 v16, -v18, v16, v12
	v_cmp_lt_f32_e64 s[12:13], 0, v16
	s_nop 1
	v_cndmask_b32_e64 v16, v17, v18, s[12:13]
	v_mul_f32_e32 v17, 0x37800000, v16
	v_cndmask_b32_e32 v16, v16, v17, vcc
	v_cmp_class_f32_e32 vcc, v12, v171
	v_or_b32_e32 v18, v30, v2
	s_nop 0
	v_cndmask_b32_e32 v12, v16, v12, vcc
	ds_read2_b32 v[16:17], v66 offset0:168 offset1:184
	s_waitcnt lgkmcnt(0)
	v_mul_f32_e32 v14, v14, v16
	v_mul_f32_e32 v12, v14, v12
	v_bfe_u32 v14, v12, 16, 1
	v_add3_u32 v12, v12, v14, s71
	global_store_short_d16_hi v[26:27], v12, off
	v_add_f32_e32 v12, v15, v23
	v_mul_f32_e32 v12, 0xbfb8aa3b, v12
	v_exp_f32_e32 v12, v12
	v_add_f32_e32 v14, v19, v22
	v_mul_f32_e32 v14, 0xbfb8aa3b, v14
	v_exp_f32_e32 v14, v14
	v_add_f32_e32 v12, 1.0, v12
	v_rcp_f32_e32 v12, v12
	v_mov_b32_e32 v19, v31
	v_add_f32_e32 v14, 1.0, v14
	v_rcp_f32_e32 v16, v14
	v_mul_f32_e32 v12, 0xc1000000, v12
	v_mul_f32_e32 v12, v12, v24
	v_mul_f32_e32 v12, 0x3fb8aa3b, v12
	v_exp_f32_e32 v12, v12
	v_lshl_add_u64 v[14:15], v[18:19], 2, s[0:1]
	v_lshl_add_u64 v[18:19], v[18:19], 1, s[4:5]
	v_fma_f32 v2, -v12, v12, 1.0
	v_max_f32_e32 v2, 0x2b8cbccc, v2
	global_store_dword v[14:15], v12, off
	v_cmp_gt_f32_e32 vcc, s18, v2
	v_mul_f32_e32 v12, 0x4f800000, v2
	s_nop 0
	v_cndmask_b32_e32 v2, v2, v12, vcc
	v_sqrt_f32_e32 v12, v2
	s_nop 0
	v_add_u32_e32 v14, -1, v12
	v_fma_f32 v15, -v14, v12, v2
	v_cmp_ge_f32_e64 s[12:13], 0, v15
	v_add_u32_e32 v15, 1, v12
	s_nop 0
	v_cndmask_b32_e64 v14, v12, v14, s[12:13]
	v_fma_f32 v12, -v15, v12, v2
	v_cmp_lt_f32_e64 s[12:13], 0, v12
	s_nop 1
	v_cndmask_b32_e64 v12, v14, v15, s[12:13]
	v_mul_f32_e32 v14, 0x37800000, v12
	v_cndmask_b32_e32 v12, v12, v14, vcc
	ds_read2_b32 v[14:15], v66 offset0:236 offset1:252
	v_cmp_class_f32_e32 vcc, v2, v171
	s_nop 1
	v_cndmask_b32_e32 v2, v12, v2, vcc
	s_waitcnt lgkmcnt(0)
	v_mul_f32_e32 v12, v16, v14
	v_mul_f32_e32 v2, v12, v2
	v_bfe_u32 v12, v2, 16, 1
	v_add3_u32 v2, v2, v12, s71
	global_store_short_d16_hi v[18:19], v2, off
	global_load_dword v14, v[40:41], off offset:192
	global_load_dword v12, v[42:43], off offset:192
	s_nop 0
	global_load_dword v18, v[34:35], off offset:192
	v_or_b32_e32 v2, s58, v61
	v_or_b32_e32 v38, v38, v2
	v_or_b32_e32 v28, v28, v2
	v_or_b32_e32 v32, v32, v2
	v_or_b32_e32 v30, v30, v2
	s_waitcnt vmcnt(2)
	v_add_f32_e32 v4, v4, v14
	v_mul_f32_e32 v4, 0xbfb8aa3b, v4
	s_waitcnt vmcnt(0)
	v_max_f32_e64 v16, -v18, -v18
	v_mul_f32_e64 v18, |v18|, s16
	v_exp_f32_e32 v20, v18
	v_exp_f32_e32 v4, v4
	v_max_f32_e32 v16, 0, v16
	v_add_f32_e32 v8, v8, v12
	v_add_f32_e32 v22, 1.0, v20
	v_add_f32_e32 v18, -1.0, v22
	v_sub_f32_e32 v19, v18, v22
	v_add_f32_e32 v19, 1.0, v19
	v_sub_f32_e32 v18, v20, v18
	v_add_f32_e32 v23, v18, v19
	v_frexp_mant_f32_e32 v18, v22
	v_cmp_gt_f32_e32 vcc, s17, v18
	v_cvt_f64_f32_e32 v[18:19], v22
	v_frexp_exp_i32_f64_e32 v18, v[18:19]
	v_subbrev_co_u32_e32 v18, vcc, 0, v18, vcc
	v_sub_u32_e32 v19, 0, v18
	v_ldexp_f32 v22, v22, v19
	v_ldexp_f32 v19, v23, v19
	v_add_f32_e32 v23, -1.0, v22
	v_add_f32_e32 v24, 1.0, v23
	v_sub_f32_e32 v24, v22, v24
	v_add_f32_e32 v24, v19, v24
	v_add_f32_e32 v25, v23, v24
	v_sub_f32_e32 v23, v25, v23
	v_sub_f32_e32 v23, v24, v23
	v_add_f32_e32 v24, 1.0, v22
	v_add_f32_e32 v26, -1.0, v24
	v_sub_f32_e32 v22, v22, v26
	v_add_f32_e32 v19, v19, v22
	v_add_f32_e32 v22, v24, v19
	v_sub_f32_e32 v24, v22, v24
	v_sub_f32_e32 v19, v19, v24
	v_rcp_f32_e32 v24, v22
	v_cvt_f32_i32_e32 v18, v18
	v_cmp_neq_f32_e32 vcc, s3, v20
	v_add_f32_e32 v4, 1.0, v4
	v_mul_f32_e32 v26, v25, v24
	v_mul_f32_e32 v27, v22, v26
	v_fma_f32 v34, v26, v22, -v27
	v_fmac_f32_e32 v34, v26, v19
	v_add_f32_e32 v35, v27, v34
	v_sub_f32_e32 v40, v25, v35
	v_sub_f32_e32 v25, v25, v40
	v_sub_f32_e32 v27, v35, v27
	v_sub_f32_e32 v25, v25, v35
	v_add_f32_e32 v23, v23, v25
	v_sub_f32_e32 v25, v27, v34
	v_add_f32_e32 v23, v25, v23
	v_add_f32_e32 v25, v40, v23
	v_mul_f32_e32 v27, v24, v25
	v_mul_f32_e32 v34, v22, v27
	v_fma_f32 v22, v27, v22, -v34
	v_fmac_f32_e32 v22, v27, v19
	v_sub_f32_e32 v19, v40, v25
	v_add_f32_e32 v19, v23, v19
	v_add_f32_e32 v23, v34, v22
	v_sub_f32_e32 v35, v25, v23
	v_sub_f32_e32 v25, v25, v35
	v_sub_f32_e32 v34, v23, v34
	v_sub_f32_e32 v23, v25, v23
	v_add_f32_e32 v19, v19, v23
	v_sub_f32_e32 v22, v34, v22
	v_add_f32_e32 v19, v22, v19
	v_add_f32_e32 v22, v26, v27
	v_add_f32_e32 v19, v35, v19
	v_sub_f32_e32 v23, v22, v26
	v_mul_f32_e32 v19, v24, v19
	v_sub_f32_e32 v23, v27, v23
	v_add_f32_e32 v19, v23, v19
	v_mul_f32_e32 v26, 0x3f317218, v18
	v_add_f32_e32 v23, v22, v19
	v_fma_f32 v27, v18, s19, -v26
; __device__ __forceinline__ float sigmoid_(float x) { return __builtin_amdgcn_rcpf(1.f + __expf(-x)); }
; __device__ __forceinline__ float softplus_(float x) { return fmaxf(x, 0.f) + log1pf(__expf(-fabsf(x))); }
; __device__ __forceinline__ unsigned f2bf(float f) { unsigned u = __builtin_bit_cast(unsigned, f); return (u + 0x7fffu + ((u >> 16) & 1u)) >> 16; }
; __device__ __forceinline__ void prep_phase(const Params& P, float* L, int l) {
;     ...
;             for (int jt = 0; jt < 4; ++jt) {
;                 const int j = jt * 16 + fr, c = h * 64 + j;
;                 const float ba1 = P.lru_ba[(size_t)(l * 2 + d) * 512 + c], bx1 = P.lru_bx[(size_t)(l * 2 + d) * 512 + c], sp = softplus_(-P.lru_lambda[(size_t)(l * 2 + d) * 512 + c]);
; #pragma unroll
;                 for (int jj = 0; jj < 4; ++jj) {
;                     const int t = tt * 16 + 4 * fq + jj, row = row0 + t;
;                     const float rg = sigmoid_(acc[0][jt][jj] + ba1), ig = sigmoid_(acc[1][jt][jj] + bx1);
;                     const float la = -8.f * rg * sp;
;                     const float a_ = __expf(la); LA[((size_t)d * MALL + row) * 512 + c] = a_;
;                     LB[((size_t)d * MALL + row) * 512 + c] = (bf16)f2bf(sqrtf(fmaxf(1.f - a_ * a_, 1e-12f)) * (ig * xs[t * 68 + j]));
;                 }
	v_mul_f32_e32 v24, v23, v23
	v_fmac_f32_e32 v27, 0xb102e308, v18
	v_sub_f32_e32 v18, v23, v22
	v_fmamk_f32 v25, v24, 0x3e9b6dac, v170
	v_sub_f32_e32 v18, v19, v18
	v_add_f32_e32 v19, v26, v27
	v_fmaak_f32 v25, v24, v25, 0x3f2aaada
	v_sub_f32_e32 v22, v19, v26
	v_ldexp_f32 v26, v23, 1
	v_mul_f32_e32 v23, v23, v24
	v_mul_f32_e32 v23, v23, v25
	v_add_f32_e32 v24, v26, v23
	v_sub_f32_e32 v25, v24, v26
	v_ldexp_f32 v18, v18, 1
	v_sub_f32_e32 v23, v23, v25
	v_add_f32_e32 v18, v18, v23
	v_add_f32_e32 v23, v24, v18
	v_sub_f32_e32 v24, v23, v24
	v_sub_f32_e32 v18, v18, v24
	v_add_f32_e32 v24, v19, v23
	v_sub_f32_e32 v25, v24, v19
	v_sub_f32_e32 v26, v24, v25
	v_sub_f32_e32 v22, v27, v22
	v_sub_f32_e32 v19, v19, v26
	v_sub_f32_e32 v23, v23, v25
	v_add_f32_e32 v19, v23, v19
	v_add_f32_e32 v23, v22, v18
	v_sub_f32_e32 v25, v23, v22
	v_sub_f32_e32 v26, v23, v25
	v_sub_f32_e32 v22, v22, v26
	v_sub_f32_e32 v18, v18, v25
	v_add_f32_e32 v19, v23, v19
	v_add_f32_e32 v18, v18, v22
	v_add_f32_e32 v22, v24, v19
	v_sub_f32_e32 v23, v22, v24
	v_sub_f32_e32 v19, v19, v23
	v_add_f32_e32 v18, v18, v19
	v_add_f32_e32 v18, v22, v18
	v_cndmask_b32_e32 v18, v187, v18, vcc
	v_cmp_ngt_f32_e32 vcc, -1.0, v20
	v_rcp_f32_e32 v4, v4
	v_mul_f32_e32 v8, 0xbfb8aa3b, v8
	v_cndmask_b32_e32 v18, v188, v18, vcc
	v_cmp_neq_f32_e32 vcc, -1.0, v20
	v_mul_f32_e32 v4, 0xc1000000, v4
	v_exp_f32_e32 v8, v8
	v_cndmask_b32_e32 v18, v189, v18, vcc
	v_cmp_lt_f32_e64 vcc, |v20|, s20
	v_add_f32_e32 v8, 1.0, v8
	s_nop 0
	v_cndmask_b32_e32 v18, v18, v20, vcc
	v_add_f32_e32 v16, v16, v18
	v_mov_b32_e32 v111, v16
	v_mul_f32_e32 v4, v4, v16
	v_mul_f32_e32 v4, 0x3fb8aa3b, v4
	v_exp_f32_e32 v4, v4
	v_lshl_add_u64 v[18:19], v[38:39], 2, s[0:1]
	v_rcp_f32_e32 v8, v8
	global_store_dword v[18:19], v4, off
	v_fma_f32 v4, -v4, v4, 1.0
	v_max_f32_e32 v4, 0x2b8cbccc, v4
	v_cmp_gt_f32_e32 vcc, s18, v4
	v_mul_f32_e32 v18, 0x4f800000, v4
	v_mul_f32_e32 v8, v21, v8
	v_cndmask_b32_e32 v4, v4, v18, vcc
	v_sqrt_f32_e32 v18, v4
	s_nop 0
	v_add_u32_e32 v19, -1, v18
	v_fma_f32 v20, -v19, v18, v4
	v_cmp_ge_f32_e64 s[12:13], 0, v20
	v_add_u32_e32 v20, 1, v18
	s_nop 0
	v_cndmask_b32_e64 v19, v18, v19, s[12:13]
	v_fma_f32 v18, -v20, v18, v4
	v_cmp_lt_f32_e64 s[12:13], 0, v18
	s_nop 1
	v_cndmask_b32_e64 v18, v19, v20, s[12:13]
	v_mul_f32_e32 v19, 0x37800000, v18
	v_cndmask_b32_e32 v18, v18, v19, vcc
	v_cmp_class_f32_e32 vcc, v4, v171
	s_nop 1
	v_cndmask_b32_e32 v4, v18, v4, vcc
	v_mul_f32_e32 v4, v8, v4
	v_bfe_u32 v8, v4, 16, 1
	v_add3_u32 v4, v4, v8, s71
	v_lshl_add_u64 v[18:19], v[38:39], 1, s[4:5]
	global_store_short_d16_hi v[18:19], v4, off
	v_add_f32_e32 v4, v5, v14
	v_mul_f32_e32 v4, 0xbfb8aa3b, v4
	v_exp_f32_e32 v4, v4
	v_add_f32_e32 v5, v9, v12
	v_mul_f32_e32 v5, 0xbfb8aa3b, v5
	v_exp_f32_e32 v5, v5
	v_add_f32_e32 v4, 1.0, v4
	v_rcp_f32_e32 v4, v4
	v_add_f32_e32 v5, 1.0, v5
	v_rcp_f32_e32 v8, v5
	v_mul_f32_e32 v4, 0xc1000000, v4
	v_mul_f32_e32 v4, v4, v16
	v_mul_f32_e32 v4, 0x3fb8aa3b, v4
	v_exp_f32_e32 v9, v4
	v_lshl_add_u64 v[4:5], v[28:29], 2, s[0:1]
	global_store_dword v[4:5], v9, off
	v_fma_f32 v4, -v9, v9, 1.0
	v_max_f32_e32 v4, 0x2b8cbccc, v4
	v_cmp_gt_f32_e32 vcc, s18, v4
	v_mul_f32_e32 v5, 0x4f800000, v4
	s_nop 0
	v_cndmask_b32_e32 v4, v4, v5, vcc
	v_sqrt_f32_e32 v5, v4
	s_nop 0
	v_add_u32_e32 v9, -1, v5
	v_fma_f32 v18, -v9, v5, v4
	v_cmp_ge_f32_e64 s[12:13], 0, v18
	v_add_u32_e32 v18, 1, v5
	s_nop 0
	v_cndmask_b32_e64 v9, v5, v9, s[12:13]
	v_fma_f32 v5, -v18, v5, v4
	v_cmp_lt_f32_e64 s[12:13], 0, v5
	s_nop 1
	v_cndmask_b32_e64 v5, v9, v18, s[12:13]
	v_mul_f32_e32 v9, 0x37800000, v5
	v_cndmask_b32_e32 v5, v5, v9, vcc
	v_cmp_class_f32_e32 vcc, v4, v171
	s_nop 1
	v_cndmask_b32_e32 v4, v5, v4, vcc
	v_mul_f32_e32 v5, v8, v13
	v_mul_f32_e32 v4, v5, v4
	v_bfe_u32 v5, v4, 16, 1
	v_add3_u32 v8, v4, v5, s71
	v_lshl_add_u64 v[4:5], v[28:29], 1, s[4:5]
	global_store_short_d16_hi v[4:5], v8, off
	v_add_f32_e32 v4, v6, v14
	v_mul_f32_e32 v4, 0xbfb8aa3b, v4
	v_exp_f32_e32 v4, v4
	v_add_f32_e32 v5, v10, v12
	v_mul_f32_e32 v5, 0xbfb8aa3b, v5
	v_exp_f32_e32 v5, v5
	v_add_f32_e32 v4, 1.0, v4
	v_rcp_f32_e32 v4, v4
	v_add_f32_e32 v5, 1.0, v5
	v_rcp_f32_e32 v6, v5
	v_mul_f32_e32 v4, 0xc1000000, v4
	v_mul_f32_e32 v4, v4, v16
	v_mul_f32_e32 v4, 0x3fb8aa3b, v4
	v_exp_f32_e32 v8, v4
	v_lshl_add_u64 v[4:5], v[32:33], 2, s[0:1]
	global_store_dword v[4:5], v8, off
	v_fma_f32 v4, -v8, v8, 1.0
	v_max_f32_e32 v4, 0x2b8cbccc, v4
	v_cmp_gt_f32_e32 vcc, s18, v4
	v_mul_f32_e32 v5, 0x4f800000, v4
	s_nop 0
	v_cndmask_b32_e32 v4, v4, v5, vcc
	v_sqrt_f32_e32 v5, v4
	s_nop 0
	v_add_u32_e32 v8, -1, v5
	v_fma_f32 v9, -v8, v5, v4
	v_cmp_ge_f32_e64 s[12:13], 0, v9
	v_add_u32_e32 v9, 1, v5
	s_nop 0
	v_cndmask_b32_e64 v8, v5, v8, s[12:13]
	v_fma_f32 v5, -v9, v5, v4
	v_cmp_lt_f32_e64 s[12:13], 0, v5
	s_nop 1
	v_cndmask_b32_e64 v5, v8, v9, s[12:13]
	v_mul_f32_e32 v8, 0x37800000, v5
	v_cndmask_b32_e32 v5, v5, v8, vcc
	v_cmp_class_f32_e32 vcc, v4, v171
	s_nop 1
	v_cndmask_b32_e32 v4, v5, v4, vcc
	v_mul_f32_e32 v5, v6, v17
	v_mul_f32_e32 v4, v5, v4
	v_bfe_u32 v5, v4, 16, 1
	v_add3_u32 v6, v4, v5, s71
	v_lshl_add_u64 v[4:5], v[32:33], 1, s[4:5]
	global_store_short_d16_hi v[4:5], v6, off
	v_add_f32_e32 v4, v7, v14
	v_mul_f32_e32 v4, 0xbfb8aa3b, v4
	v_exp_f32_e32 v4, v4
	v_add_f32_e32 v5, v11, v12
	v_mul_f32_e32 v5, 0xbfb8aa3b, v5
	v_exp_f32_e32 v5, v5
	v_add_f32_e32 v4, 1.0, v4
	v_rcp_f32_e32 v4, v4
	v_add_f32_e32 v5, 1.0, v5
	v_rcp_f32_e32 v6, v5
	v_mul_f32_e32 v4, 0xc1000000, v4
	v_mul_f32_e32 v4, v4, v16
	v_mul_f32_e32 v4, 0x3fb8aa3b, v4
	v_exp_f32_e32 v7, v4
	v_lshl_add_u64 v[4:5], v[30:31], 2, s[0:1]
	v_fma_f32 v2, -v7, v7, 1.0
	v_max_f32_e32 v2, 0x2b8cbccc, v2
	global_store_dword v[4:5], v7, off
	v_cmp_gt_f32_e32 vcc, s18, v2
	v_mul_f32_e32 v4, 0x4f800000, v2
	s_nop 0
	v_cndmask_b32_e32 v2, v2, v4, vcc
	v_sqrt_f32_e32 v4, v2
	s_nop 0
	v_add_u32_e32 v5, -1, v4
	v_fma_f32 v7, -v5, v4, v2
	v_cmp_ge_f32_e64 s[12:13], 0, v7
	v_add_u32_e32 v7, 1, v4
	s_nop 0
	v_cndmask_b32_e64 v5, v4, v5, s[12:13]
	v_fma_f32 v4, -v7, v4, v2
	v_cmp_lt_f32_e64 s[12:13], 0, v4
	s_nop 1
	v_cndmask_b32_e64 v4, v5, v7, s[12:13]
	v_mul_f32_e32 v5, 0x37800000, v4
	v_cndmask_b32_e32 v4, v4, v5, vcc
	v_cmp_class_f32_e32 vcc, v2, v171
	v_readlane_b32 s12, v254, 18
	v_readlane_b32 s13, v254, 19
	v_cndmask_b32_e32 v2, v4, v2, vcc
	v_mul_f32_e32 v4, v6, v15
	v_mul_f32_e32 v2, v4, v2
	v_bfe_u32 v4, v2, 16, 1
	v_add3_u32 v2, v2, v4, s71
	v_lshl_add_u64 v[4:5], v[30:31], 1, s[4:5]
	global_store_short_d16_hi v[4:5], v2, off
	s_load_dword s12, s[12:13], 0x0
	s_waitcnt lgkmcnt(0)
	s_add_i32 s34, s34, s12
	s_cmpk_gt_i32 s34, 0x47f
	s_branch .Lprepe_join
; __device__ __forceinline__ float sigmoid_(float x) { return __builtin_amdgcn_rcpf(1.f + __expf(-x)); }
; __device__ __forceinline__ float softplus_(float x) { return fmaxf(x, 0.f) + log1pf(__expf(-fabsf(x))); }
; __device__ __forceinline__ void prep_phase(const Params& P, float* L, int l) {
;     ...
;         {
;             const int tt = wave & 3, d = wave >> 2;
;             f32x4 acc[2][4];
; #pragma unroll
;             for (int g2 = 0; g2 < 2; ++g2)
; #pragma unroll
;                 for (int jt = 0; jt < 4; ++jt) acc[g2][jt] = (f32x4){0.f, 0.f, 0.f, 0.f};
; #pragma unroll
;             for (int ks = 0; ks < 2; ++ks) {
;                 const bf16x8_t a = *(const bf16x8_t*)&xb[(tt * 16 + fr) * 72 + ks * 32 + fq * 8];
; #pragma unroll
;                 for (int g2 = 0; g2 < 2; ++g2)
; #pragma unroll
;                     for (int jt = 0; jt < 4; ++jt) { const bf16x8_t bq = *(const bf16x8_t*)&WT[((d * 2 + g2) * 64 + jt * 16 + fr) * 72 + ks * 32 + fq * 8];
;                         acc[g2][jt] = __builtin_amdgcn_mfma_f32_16x16x32_bf16(a, bq, acc[g2][jt], 0, 0, 0); }
;             }
; #pragma unroll
;             for (int jt = 0; jt < 4; ++jt) {
;                 const int j = jt * 16 + fr, c = h * 64 + j;
;                 const float ba1 = P.lru_ba[(size_t)(l * 2 + d) * 512 + c], bx1 = P.lru_bx[(size_t)(l * 2 + d) * 512 + c], sp = softplus_(-P.lru_lambda[(size_t)(l * 2 + d) * 512 + c]);
; #pragma unroll
;                 for (int jj = 0; jj < 4; ++jj) {
;                     const int t = tt * 16 + 4 * fq + jj, row = row0 + t;
;                     const float rg = sigmoid_(acc[0][jt][jj] + ba1), ig = sigmoid_(acc[1][jt][jj] + bx1);
;                     const float la = -8.f * rg * sp;
;                     const float a_ = __expf(la); LA[((size_t)d * MALL + row) * 512 + c] = a_;
.Lprepe_fast:
	v_mfma_f32_16x16x32_bf16 v[46:49], v[4:7], v[20:23], 0
	ds_read_b128 v[20:23], v64 offset:16128
	v_readlane_b32 s29, v255, 11
	v_readlane_b32 s61, v254, 55
	v_mfma_f32_16x16x32_bf16 v[8:11], v[4:7], v[8:11], 0
	v_readlane_b32 s62, v254, 56
	v_readlane_b32 s63, v254, 57
	s_mov_b32 s16, 0xbfb8aa3b
	v_mfma_f32_16x16x32_bf16 v[12:15], v[4:7], v[12:15], 0
	v_readlane_b32 s17, v254, 63
	s_mov_b32 s17, 0x3f2aaaab
	v_readlane_b32 s19, v255, 1
	v_mfma_f32_16x16x32_bf16 v[16:19], v[4:7], v[16:19], 0
	s_mov_b32 s19, 0x3f317218
	s_mov_b32 s3, 0x7f800000
	v_readlane_b32 s20, v255, 2
	s_waitcnt lgkmcnt(0)
	v_mfma_f32_16x16x32_bf16 v[66:69], v[4:7], v[20:23], 0
	ds_read_b128 v[70:73], v54 offset:36928
	ds_read_b128 v[4:7], v64 offset:64
	s_mov_b32 s20, 0x33800000
	v_or_b32_e32 v38, s49, v55
	s_waitcnt lgkmcnt(0)
	v_mfma_f32_16x16x32_bf16 v[28:31], v[70:73], v[4:7], v[8:11]
	ds_read_b128 v[4:7], v64 offset:2368
	s_nop 1
	ds_read_b128 v[8:11], v64 offset:9280
	v_readlane_b32 s18, v255, 0
	s_waitcnt lgkmcnt(1)
	v_mfma_f32_16x16x32_bf16 v[20:23], v[70:73], v[4:7], v[12:15]
	ds_read_b128 v[4:7], v64 offset:4672
	s_mov_b32 s18, 0xf800000
	v_readlane_b32 s56, v255, 30
	s_waitcnt lgkmcnt(1)
	v_mfma_f32_16x16x32_bf16 v[32:35], v[70:73], v[8:11], v[32:35]
	ds_read_b128 v[8:11], v64 offset:11584
	v_readlane_b32 s57, v255, 31
	v_readlane_b32 s21, v255, 3
	s_waitcnt lgkmcnt(1)
	v_mfma_f32_16x16x32_bf16 v[12:15], v[70:73], v[4:7], v[16:19]
	ds_read_b128 v[4:7], v64 offset:6976
	v_readlane_b32 s22, v255, 4
	v_readlane_b32 s23, v255, 5
	s_waitcnt lgkmcnt(0)
	v_mfma_f32_16x16x32_bf16 v[4:7], v[70:73], v[4:7], v[24:27]
	v_readlane_b32 s24, v255, 6
	v_readlane_b32 s25, v255, 7
	v_readlane_b32 s26, v255, 8
	v_mfma_f32_16x16x32_bf16 v[24:27], v[70:73], v[8:11], v[42:45]
	ds_read_b128 v[8:11], v64 offset:13888
	v_readlane_b32 s27, v255, 9
	v_readlane_b32 s30, v255, 12
	v_or_b32_e32 v42, s80, v2
	v_mov_b32_e32 v43, s81
	v_lshlrev_b64 v[44:45], 2, v[42:43]
	s_waitcnt lgkmcnt(0)
	v_mfma_f32_16x16x32_bf16 v[16:19], v[70:73], v[8:11], v[46:49]
	v_lshl_add_u64 v[42:43], s[28:29], 0, v[44:45]
	global_load_dword v42, v[42:43], off
	ds_read_b128 v[8:11], v64 offset:16192
	v_lshl_add_u64 v[46:47], s[60:61], 0, v[44:45]
	global_load_dword v41, v[46:47], off
	s_waitcnt lgkmcnt(0)
	v_mfma_f32_16x16x32_bf16 v[8:11], v[70:73], v[8:11], v[66:69]
	v_readlane_b32 s31, v255, 13
	v_readlane_b32 s64, v254, 58
	v_readlane_b32 s65, v254, 59
	v_readlane_b32 s66, v254, 60
	v_readlane_b32 s67, v254, 61
	s_waitcnt vmcnt(1)
	v_add_f32_e32 v28, v28, v42
	v_mul_f32_e32 v28, 0xbfb8aa3b, v28
	v_exp_f32_e32 v28, v28
	v_add_f32_e32 v29, v29, v42
	v_add_f32_e32 v28, 1.0, v28
	v_rcp_f32_e32 v28, v28
	s_nop 0
	v_mul_f32_e32 v28, 0xc1000000, v28
	s_waitcnt vmcnt(0)
	v_add_f32_e32 v32, v32, v41
	v_mul_f32_e32 v32, 0xbfb8aa3b, v32
	v_exp_f32_e32 v32, v32
	v_add_u32_e32 v66, 0xb400, v65
	v_mul_f32_e32 v29, 0xbfb8aa3b, v29
	v_add_f32_e32 v32, 1.0, v32
	v_mov_b32_e32 v43, v108
	v_mul_f32_e32 v28, v28, v43
	v_mul_f32_e32 v28, 0x3fb8aa3b, v28
	v_ashrrev_i32_e32 v39, 31, v38
	v_exp_f32_e32 v28, v28
	v_lshl_add_u64 v[38:39], s[86:87], 0, v[38:39]
	v_lshlrev_b64 v[38:39], 9, v[38:39]
	v_or_b32_e32 v44, v38, v2
	v_mov_b32_e32 v45, v39
	v_lshl_add_u64 v[46:47], v[44:45], 2, s[0:1]
	global_store_dword v[46:47], v28, off
	v_fma_f32 v28, -v28, v28, 1.0
	v_max_f32_e32 v28, 0x2b8cbccc, v28
	v_cmp_gt_f32_e32 vcc, s18, v28
	v_mul_f32_e32 v46, 0x4f800000, v28
	v_exp_f32_e32 v29, v29
	v_cndmask_b32_e32 v28, v28, v46, vcc
	v_sqrt_f32_e32 v46, v28
	v_rcp_f32_e32 v32, v32
	v_add_f32_e32 v29, 1.0, v29
	v_rcp_f32_e32 v29, v29
	v_add_u32_e32 v47, -1, v46
	v_fma_f32 v48, -v47, v46, v28
	v_cmp_ge_f32_e64 s[12:13], 0, v48
	v_add_u32_e32 v48, 1, v46
	v_mul_f32_e32 v29, 0xc1000000, v29
	v_cndmask_b32_e64 v47, v46, v47, s[12:13]
	v_fma_f32 v46, -v48, v46, v28
	v_cmp_lt_f32_e64 s[12:13], 0, v46
	v_lshl_add_u64 v[44:45], v[44:45], 1, s[4:5]
	v_mul_f32_e32 v29, v29, v43
	v_cndmask_b32_e64 v46, v47, v48, s[12:13]
	v_mul_f32_e32 v47, 0x37800000, v46
	v_cndmask_b32_e32 v46, v46, v47, vcc
	v_cmp_class_f32_e32 vcc, v28, v171
	v_mul_f32_e32 v29, 0x3fb8aa3b, v29
	v_exp_f32_e32 v48, v29
	v_cndmask_b32_e32 v28, v46, v28, vcc
	ds_read2_b32 v[46:47], v66 offset1:16
	v_add_f32_e32 v30, v30, v42
	v_mul_f32_e32 v30, 0xbfb8aa3b, v30
	v_exp_f32_e32 v30, v30
	v_add_f32_e32 v31, v31, v42
	s_waitcnt lgkmcnt(0)
	v_mul_f32_e32 v32, v46, v32
	v_mul_f32_e32 v28, v32, v28
	v_bfe_u32 v32, v28, 16, 1
	v_add3_u32 v28, v28, v32, s71
	v_add_f32_e32 v32, v33, v41
	v_mul_f32_e32 v32, 0xbfb8aa3b, v32
	v_exp_f32_e32 v32, v32
	global_store_short_d16_hi v[44:45], v28, off
	v_or_b32_e32 v28, s49, v56
	v_ashrrev_i32_e32 v29, 31, v28
	v_lshl_add_u64 v[28:29], s[86:87], 0, v[28:29]
	v_add_f32_e32 v32, 1.0, v32
	v_lshlrev_b64 v[28:29], 9, v[28:29]
	v_rcp_f32_e32 v46, v32
	v_or_b32_e32 v32, v28, v2
	v_mov_b32_e32 v33, v29
	v_lshl_add_u64 v[44:45], v[32:33], 2, s[0:1]
	global_store_dword v[44:45], v48, off
	v_fma_f32 v44, -v48, v48, 1.0
	v_max_f32_e32 v44, 0x2b8cbccc, v44
	v_cmp_gt_f32_e32 vcc, s18, v44
	v_mul_f32_e32 v45, 0x4f800000, v44
	v_lshl_add_u64 v[32:33], v[32:33], 1, s[4:5]
	v_cndmask_b32_e32 v44, v44, v45, vcc
	v_sqrt_f32_e32 v45, v44
	v_add_f32_e32 v30, 1.0, v30
	v_rcp_f32_e32 v30, v30
	v_mul_f32_e32 v31, 0xbfb8aa3b, v31
	v_add_u32_e32 v48, -1, v45
	v_fma_f32 v49, -v48, v45, v44
	v_cmp_ge_f32_e64 s[12:13], 0, v49
	v_add_u32_e32 v49, 1, v45
	v_mul_f32_e32 v30, 0xc1000000, v30
	v_cndmask_b32_e64 v48, v45, v48, s[12:13]
	v_fma_f32 v45, -v49, v45, v44
	v_cmp_lt_f32_e64 s[12:13], 0, v45
	v_mul_f32_e32 v30, v30, v43
	v_mul_f32_e32 v30, 0x3fb8aa3b, v30
	v_cndmask_b32_e64 v45, v48, v49, s[12:13]
	v_mul_f32_e32 v48, 0x37800000, v45
	v_cndmask_b32_e32 v45, v45, v48, vcc
	ds_read2_b32 v[48:49], v66 offset0:68 offset1:84
	v_cmp_class_f32_e32 vcc, v44, v171
	v_exp_f32_e32 v30, v30
	v_exp_f32_e32 v31, v31
	v_cndmask_b32_e32 v44, v45, v44, vcc
	s_waitcnt lgkmcnt(0)
; __device__ __forceinline__ float sigmoid_(float x) { return __builtin_amdgcn_rcpf(1.f + __expf(-x)); }
; __device__ __forceinline__ float softplus_(float x) { return fmaxf(x, 0.f) + log1pf(__expf(-fabsf(x))); }
; __device__ __forceinline__ unsigned f2bf(float f) { unsigned u = __builtin_bit_cast(unsigned, f); return (u + 0x7fffu + ((u >> 16) & 1u)) >> 16; }
; __device__ __forceinline__ void prep_phase(const Params& P, float* L, int l) {
;     ...
;             for (int jt = 0; jt < 4; ++jt) {
;                 const int j = jt * 16 + fr, c = h * 64 + j;
;                 const float ba1 = P.lru_ba[(size_t)(l * 2 + d) * 512 + c], bx1 = P.lru_bx[(size_t)(l * 2 + d) * 512 + c], sp = softplus_(-P.lru_lambda[(size_t)(l * 2 + d) * 512 + c]);
; #pragma unroll
;                 for (int jj = 0; jj < 4; ++jj) {
;                     const int t = tt * 16 + 4 * fq + jj, row = row0 + t;
;                     const float rg = sigmoid_(acc[0][jt][jj] + ba1), ig = sigmoid_(acc[1][jt][jj] + bx1);
;                     const float la = -8.f * rg * sp;
;                     const float a_ = __expf(la); LA[((size_t)d * MALL + row) * 512 + c] = a_;
;                     LB[((size_t)d * MALL + row) * 512 + c] = (bf16)f2bf(sqrtf(fmaxf(1.f - a_ * a_, 1e-12f)) * (ig * xs[t * 68 + j]));
;                 }
	v_mul_f32_e32 v45, v46, v48
	v_mul_f32_e32 v44, v45, v44
	v_bfe_u32 v45, v44, 16, 1
	v_add3_u32 v44, v44, v45, s71
	global_store_short_d16_hi v[32:33], v44, off
	v_add_f32_e32 v33, v34, v41
	v_mul_f32_e32 v33, 0xbfb8aa3b, v33
	v_exp_f32_e32 v33, v33
	v_or_b32_e32 v32, s49, v57
	v_add_f32_e32 v31, 1.0, v31
	v_rcp_f32_e32 v31, v31
	v_add_f32_e32 v33, 1.0, v33
	v_rcp_f32_e32 v34, v33
	v_ashrrev_i32_e32 v33, 31, v32
	v_lshl_add_u64 v[32:33], s[86:87], 0, v[32:33]
	v_lshlrev_b64 v[32:33], 9, v[32:33]
	v_or_b32_e32 v50, v32, v2
	v_mov_b32_e32 v51, v33
	v_lshl_add_u64 v[44:45], v[50:51], 2, s[0:1]
	global_store_dword v[44:45], v30, off
	v_fma_f32 v30, -v30, v30, 1.0
	v_max_f32_e32 v30, 0x2b8cbccc, v30
	v_cmp_gt_f32_e32 vcc, s18, v30
	v_mul_f32_e32 v44, 0x4f800000, v30
	v_mul_f32_e32 v31, 0xc1000000, v31
	v_cndmask_b32_e32 v30, v30, v44, vcc
	v_sqrt_f32_e32 v44, v30
	v_mul_f32_e32 v31, v31, v43
	v_lshl_add_u64 v[50:51], v[50:51], 1, s[4:5]
	v_mul_f32_e32 v31, 0x3fb8aa3b, v31
	v_add_u32_e32 v45, -1, v44
	v_fma_f32 v46, -v45, v44, v30
	v_cmp_ge_f32_e64 s[12:13], 0, v46
	v_add_u32_e32 v46, 1, v44
	s_nop 0
	v_cndmask_b32_e64 v45, v44, v45, s[12:13]
	v_fma_f32 v44, -v46, v44, v30
	v_cmp_lt_f32_e64 s[12:13], 0, v44
	s_nop 1
	v_cndmask_b32_e64 v44, v45, v46, s[12:13]
	v_mul_f32_e32 v45, 0x37800000, v44
	v_cndmask_b32_e32 v44, v44, v45, vcc
	v_cmp_class_f32_e32 vcc, v30, v171
	s_nop 1
	v_cndmask_b32_e32 v30, v44, v30, vcc
	ds_read2_b32 v[44:45], v66 offset0:136 offset1:152
	s_waitcnt lgkmcnt(0)
	v_mul_f32_e32 v34, v34, v44
	v_mul_f32_e32 v30, v34, v30
	v_bfe_u32 v34, v30, 16, 1
	v_add3_u32 v30, v30, v34, s71
	v_add_f32_e32 v34, v35, v41
	v_mul_f32_e32 v34, 0xbfb8aa3b, v34
	v_exp_f32_e32 v34, v34
	global_store_short_d16_hi v[50:51], v30, off
	v_or_b32_e32 v30, s49, v58
	v_exp_f32_e32 v44, v31
	v_ashrrev_i32_e32 v31, 31, v30
	v_lshl_add_u64 v[30:31], s[86:87], 0, v[30:31]
	v_add_f32_e32 v34, 1.0, v34
	v_lshlrev_b64 v[30:31], 9, v[30:31]
	v_rcp_f32_e32 v41, v34
	v_or_b32_e32 v34, v30, v2
	v_mov_b32_e32 v35, v31
	v_fma_f32 v2, -v44, v44, 1.0
	v_lshl_add_u64 v[42:43], v[34:35], 2, s[0:1]
	v_max_f32_e32 v2, 0x2b8cbccc, v2
	global_store_dword v[42:43], v44, off
	v_cmp_gt_f32_e32 vcc, s18, v2
	v_mul_f32_e32 v42, 0x4f800000, v2
	ds_read2_b32 v[50:51], v66 offset0:204 offset1:220
	v_cndmask_b32_e32 v2, v2, v42, vcc
	v_sqrt_f32_e32 v42, v2
	v_lshl_add_u64 v[34:35], v[34:35], 1, s[4:5]
	s_waitcnt lgkmcnt(0)
	v_mul_f32_e32 v41, v41, v50
	v_add_u32_e32 v43, -1, v42
	v_fma_f32 v44, -v43, v42, v2
	v_cmp_ge_f32_e64 s[12:13], 0, v44
	v_add_u32_e32 v44, 1, v42
	s_nop 0
	v_cndmask_b32_e64 v43, v42, v43, s[12:13]
	v_fma_f32 v42, -v44, v42, v2
	v_cmp_lt_f32_e64 s[12:13], 0, v42
	s_nop 1
	v_cndmask_b32_e64 v42, v43, v44, s[12:13]
	v_mul_f32_e32 v43, 0x37800000, v42
	v_cndmask_b32_e32 v42, v42, v43, vcc
	v_cmp_class_f32_e32 vcc, v2, v171
	v_or_b32_e32 v44, s58, v59
	s_nop 0
	v_cndmask_b32_e32 v2, v42, v2, vcc
	v_mul_f32_e32 v2, v41, v2
	v_bfe_u32 v41, v2, 16, 1
	v_add3_u32 v2, v2, v41, s71
	global_store_short_d16_hi v[34:35], v2, off
	v_add_u32_e32 v2, v40, v53
	v_lshl_add_u64 v[34:35], s[80:81], 0, v[2:3]
	v_lshlrev_b64 v[34:35], 2, v[34:35]
	v_lshl_add_u64 v[40:41], s[28:29], 0, v[34:35]
	v_lshl_add_u64 v[42:43], s[60:61], 0, v[34:35]
	v_lshl_add_u64 v[34:35], s[62:63], 0, v[34:35]
	global_load_dword v46, v[40:41], off offset:64
	global_load_dword v2, v[42:43], off offset:64
	s_waitcnt vmcnt(1)
	v_add_f32_e32 v20, v20, v46
	v_mul_f32_e32 v20, 0xbfb8aa3b, v20
	v_exp_f32_e32 v20, v20
	s_nop 0
	v_add_f32_e32 v20, 1.0, v20
	v_rcp_f32_e32 v20, v20
	s_nop 0
	v_mul_f32_e32 v20, 0xc1000000, v20
	v_or_b32_e32 v68, v38, v44
	v_mov_b32_e32 v69, v39
	v_lshl_add_u64 v[70:71], v[68:69], 2, s[0:1]
	v_mov_b32_e32 v48, v109
	v_mul_f32_e32 v20, v20, v48
	v_mul_f32_e32 v20, 0x3fb8aa3b, v20
	v_exp_f32_e32 v20, v20
	s_waitcnt vmcnt(0)
	v_add_f32_e32 v24, v24, v2
	v_mul_f32_e32 v24, 0xbfb8aa3b, v24
	v_exp_f32_e32 v24, v24
	global_store_dword v[70:71], v20, off
	v_fma_f32 v20, -v20, v20, 1.0
	v_max_f32_e32 v20, 0x2b8cbccc, v20
	v_cmp_gt_f32_e32 vcc, s18, v20
	v_mul_f32_e32 v50, 0x4f800000, v20
	v_add_f32_e32 v24, 1.0, v24
	v_cndmask_b32_e32 v20, v20, v50, vcc
	v_sqrt_f32_e32 v50, v20
	v_rcp_f32_e32 v24, v24
	v_lshl_add_u64 v[68:69], v[68:69], 1, s[4:5]
	v_add_u32_e32 v67, -1, v50
	v_fma_f32 v70, -v67, v50, v20
	v_cmp_ge_f32_e64 s[12:13], 0, v70
	v_add_u32_e32 v70, 1, v50
	v_mul_f32_e32 v24, v47, v24
	v_cndmask_b32_e64 v67, v50, v67, s[12:13]
	v_fma_f32 v50, -v70, v50, v20
	v_cmp_lt_f32_e64 s[12:13], 0, v50
	s_nop 1
	v_cndmask_b32_e64 v50, v67, v70, s[12:13]
	v_mul_f32_e32 v67, 0x37800000, v50
	v_cndmask_b32_e32 v50, v50, v67, vcc
	v_cmp_class_f32_e32 vcc, v20, v171
	s_nop 1
	v_cndmask_b32_e32 v20, v50, v20, vcc
	v_mul_f32_e32 v20, v24, v20
	v_bfe_u32 v24, v20, 16, 1
	v_add3_u32 v20, v20, v24, s71
	global_store_short_d16_hi v[68:69], v20, off
	v_add_f32_e32 v20, v21, v46
	v_mul_f32_e32 v20, 0xbfb8aa3b, v20
	v_exp_f32_e32 v20, v20
	v_add_f32_e32 v21, v25, v2
	v_mul_f32_e32 v21, 0xbfb8aa3b, v21
	v_exp_f32_e32 v21, v21
	v_add_f32_e32 v20, 1.0, v20
	v_rcp_f32_e32 v20, v20
	v_add_f32_e32 v21, 1.0, v21
	v_rcp_f32_e32 v47, v21
	v_mul_f32_e32 v20, 0xc1000000, v20
	v_mul_f32_e32 v20, v20, v48
	v_mul_f32_e32 v20, 0x3fb8aa3b, v20
	v_exp_f32_e32 v50, v20
	v_or_b32_e32 v20, v28, v44
	v_mov_b32_e32 v21, v29
	v_lshl_add_u64 v[24:25], v[20:21], 2, s[0:1]
	global_store_dword v[24:25], v50, off
	v_fma_f32 v24, -v50, v50, 1.0
	v_max_f32_e32 v24, 0x2b8cbccc, v24
	v_cmp_gt_f32_e32 vcc, s18, v24
	v_mul_f32_e32 v25, 0x4f800000, v24
	v_lshl_add_u64 v[20:21], v[20:21], 1, s[4:5]
	v_cndmask_b32_e32 v24, v24, v25, vcc
; __device__ __forceinline__ float sigmoid_(float x) { return __builtin_amdgcn_rcpf(1.f + __expf(-x)); }
; __device__ __forceinline__ float softplus_(float x) { return fmaxf(x, 0.f) + log1pf(__expf(-fabsf(x))); }
; __device__ __forceinline__ unsigned f2bf(float f) { unsigned u = __builtin_bit_cast(unsigned, f); return (u + 0x7fffu + ((u >> 16) & 1u)) >> 16; }
; __device__ __forceinline__ void prep_phase(const Params& P, float* L, int l) {
;     ...
;             for (int jt = 0; jt < 4; ++jt) {
;                 const int j = jt * 16 + fr, c = h * 64 + j;
;                 const float ba1 = P.lru_ba[(size_t)(l * 2 + d) * 512 + c], bx1 = P.lru_bx[(size_t)(l * 2 + d) * 512 + c], sp = softplus_(-P.lru_lambda[(size_t)(l * 2 + d) * 512 + c]);
; #pragma unroll
;                 for (int jj = 0; jj < 4; ++jj) {
;                     const int t = tt * 16 + 4 * fq + jj, row = row0 + t;
;                     const float rg = sigmoid_(acc[0][jt][jj] + ba1), ig = sigmoid_(acc[1][jt][jj] + bx1);
;                     const float la = -8.f * rg * sp;
;                     const float a_ = __expf(la); LA[((size_t)d * MALL + row) * 512 + c] = a_;
;                     LB[((size_t)d * MALL + row) * 512 + c] = (bf16)f2bf(sqrtf(fmaxf(1.f - a_ * a_, 1e-12f)) * (ig * xs[t * 68 + j]));
;                 }
	v_sqrt_f32_e32 v25, v24
	s_nop 0
	v_add_u32_e32 v50, -1, v25
	v_fma_f32 v67, -v50, v25, v24
	v_cmp_ge_f32_e64 s[12:13], 0, v67
	v_add_u32_e32 v67, 1, v25
	s_nop 0
	v_cndmask_b32_e64 v50, v25, v50, s[12:13]
	v_fma_f32 v25, -v67, v25, v24
	v_cmp_lt_f32_e64 s[12:13], 0, v25
	s_nop 1
	v_cndmask_b32_e64 v25, v50, v67, s[12:13]
	v_mul_f32_e32 v50, 0x37800000, v25
	v_cndmask_b32_e32 v25, v25, v50, vcc
	v_cmp_class_f32_e32 vcc, v24, v171
	s_nop 1
	v_cndmask_b32_e32 v24, v25, v24, vcc
	v_mul_f32_e32 v25, v47, v49
	v_mul_f32_e32 v24, v25, v24
	v_bfe_u32 v25, v24, 16, 1
	v_add3_u32 v24, v24, v25, s71
	global_store_short_d16_hi v[20:21], v24, off
	v_add_f32_e32 v20, v22, v46
	v_mul_f32_e32 v20, 0xbfb8aa3b, v20
	v_exp_f32_e32 v20, v20
	v_add_f32_e32 v21, v26, v2
	v_mul_f32_e32 v21, 0xbfb8aa3b, v21
	v_exp_f32_e32 v21, v21
	v_add_f32_e32 v20, 1.0, v20
	v_rcp_f32_e32 v20, v20
	v_add_f32_e32 v2, v27, v2
	v_add_f32_e32 v21, 1.0, v21
	v_rcp_f32_e32 v22, v21
	v_mul_f32_e32 v20, 0xc1000000, v20
	v_mul_f32_e32 v20, v20, v48
	v_mul_f32_e32 v20, 0x3fb8aa3b, v20
	v_exp_f32_e32 v26, v20
	v_or_b32_e32 v20, v32, v44
	v_mov_b32_e32 v21, v33
	v_lshl_add_u64 v[24:25], v[20:21], 2, s[0:1]
	global_store_dword v[24:25], v26, off
	v_fma_f32 v24, -v26, v26, 1.0
	v_max_f32_e32 v24, 0x2b8cbccc, v24
	v_cmp_gt_f32_e32 vcc, s18, v24
	v_mul_f32_e32 v25, 0x4f800000, v24
	v_mul_f32_e32 v22, v22, v45
	v_cndmask_b32_e32 v24, v24, v25, vcc
	v_sqrt_f32_e32 v25, v24
	v_lshl_add_u64 v[20:21], v[20:21], 1, s[4:5]
	v_mul_f32_e32 v2, 0xbfb8aa3b, v2
	v_exp_f32_e32 v2, v2
	v_add_u32_e32 v26, -1, v25
	v_fma_f32 v47, -v26, v25, v24
	v_cmp_ge_f32_e64 s[12:13], 0, v47
	v_add_u32_e32 v47, 1, v25
	v_add_f32_e32 v2, 1.0, v2
	v_cndmask_b32_e64 v26, v25, v26, s[12:13]
	v_fma_f32 v25, -v47, v25, v24
	v_cmp_lt_f32_e64 s[12:13], 0, v25
	v_rcp_f32_e32 v2, v2
	s_nop 0
	v_cndmask_b32_e64 v25, v26, v47, s[12:13]
	v_mul_f32_e32 v26, 0x37800000, v25
	v_cndmask_b32_e32 v25, v25, v26, vcc
	v_cmp_class_f32_e32 vcc, v24, v171
	v_mul_f32_e32 v2, v2, v51
	s_nop 0
	v_cndmask_b32_e32 v24, v25, v24, vcc
	v_mul_f32_e32 v22, v22, v24
	v_bfe_u32 v24, v22, 16, 1
	v_add3_u32 v22, v22, v24, s71
	global_store_short_d16_hi v[20:21], v22, off
	v_add_f32_e32 v20, v23, v46
	v_mul_f32_e32 v20, 0xbfb8aa3b, v20
	v_exp_f32_e32 v20, v20
	v_mov_b32_e32 v21, v31
	v_add_f32_e32 v20, 1.0, v20
	v_rcp_f32_e32 v20, v20
	s_nop 0
	v_mul_f32_e32 v20, 0xc1000000, v20
	v_mul_f32_e32 v20, v20, v48
	v_mul_f32_e32 v20, 0x3fb8aa3b, v20
	v_exp_f32_e32 v24, v20
	v_or_b32_e32 v20, v30, v44
	v_lshl_add_u64 v[22:23], v[20:21], 2, s[0:1]
	v_lshl_add_u64 v[20:21], v[20:21], 1, s[4:5]
	global_store_dword v[22:23], v24, off
	v_fma_f32 v22, -v24, v24, 1.0
	v_max_f32_e32 v22, 0x2b8cbccc, v22
	v_cmp_gt_f32_e32 vcc, s18, v22
	v_mul_f32_e32 v23, 0x4f800000, v22
	s_nop 0
	v_cndmask_b32_e32 v22, v22, v23, vcc
	v_sqrt_f32_e32 v23, v22
	s_nop 0
	v_add_u32_e32 v24, -1, v23
	v_fma_f32 v25, -v24, v23, v22
	v_cmp_ge_f32_e64 s[12:13], 0, v25
	v_add_u32_e32 v25, 1, v23
	s_nop 0
	v_cndmask_b32_e64 v24, v23, v24, s[12:13]
	v_fma_f32 v23, -v25, v23, v22
	v_cmp_lt_f32_e64 s[12:13], 0, v23
	s_nop 1
	v_cndmask_b32_e64 v23, v24, v25, s[12:13]
	v_mul_f32_e32 v24, 0x37800000, v23
	v_cndmask_b32_e32 v23, v23, v24, vcc
	v_cmp_class_f32_e32 vcc, v22, v171
	s_nop 1
	v_cndmask_b32_e32 v22, v23, v22, vcc
	v_mul_f32_e32 v2, v2, v22
	v_bfe_u32 v22, v2, 16, 1
	v_add3_u32 v2, v2, v22, s71
	global_store_short_d16_hi v[20:21], v2, off
	global_load_dword v23, v[40:41], off offset:128
	global_load_dword v22, v[42:43], off offset:128
	s_nop 0
	global_load_dword v20, v[34:35], off offset:128
	v_or_b32_e32 v2, s58, v60
	s_waitcnt vmcnt(2)
	v_add_f32_e32 v12, v12, v23
	v_mul_f32_e32 v12, 0xbfb8aa3b, v12
	s_waitcnt vmcnt(0)
	v_mul_f32_e64 v20, |v20|, s16
	v_exp_f32_e32 v25, v20
	v_exp_f32_e32 v12, v12
	v_add_f32_e32 v16, v16, v22
	v_add_f32_e32 v26, 1.0, v25
	v_add_f32_e32 v20, -1.0, v26
	v_sub_f32_e32 v21, v20, v26
	v_add_f32_e32 v21, 1.0, v21
	v_sub_f32_e32 v20, v25, v20
	v_add_f32_e32 v27, v20, v21
	v_frexp_mant_f32_e32 v20, v26
	v_cmp_gt_f32_e32 vcc, s17, v20
	v_cvt_f64_f32_e32 v[20:21], v26
	v_frexp_exp_i32_f64_e32 v20, v[20:21]
	v_subbrev_co_u32_e32 v20, vcc, 0, v20, vcc
	v_sub_u32_e32 v21, 0, v20
	v_ldexp_f32 v26, v26, v21
	v_ldexp_f32 v21, v27, v21
	v_add_f32_e32 v27, -1.0, v26
	v_add_f32_e32 v44, 1.0, v27
	v_sub_f32_e32 v44, v26, v44
	v_add_f32_e32 v44, v21, v44
	v_add_f32_e32 v45, v27, v44
	v_sub_f32_e32 v27, v45, v27
	v_sub_f32_e32 v27, v44, v27
	v_add_f32_e32 v44, 1.0, v26
	v_add_f32_e32 v46, -1.0, v44
	v_sub_f32_e32 v26, v26, v46
	v_add_f32_e32 v21, v21, v26
	v_add_f32_e32 v26, v44, v21
	v_sub_f32_e32 v44, v26, v44
	v_sub_f32_e32 v21, v21, v44
	v_rcp_f32_e32 v44, v26
	v_cvt_f32_i32_e32 v20, v20
	v_add_f32_e32 v12, 1.0, v12
	v_mul_f32_e32 v46, v45, v44
	v_mul_f32_e32 v47, v26, v46
	v_fma_f32 v48, v46, v26, -v47
	v_fmac_f32_e32 v48, v46, v21
	v_add_f32_e32 v49, v47, v48
	v_sub_f32_e32 v50, v45, v49
	v_sub_f32_e32 v45, v45, v50
	v_sub_f32_e32 v47, v49, v47
	v_sub_f32_e32 v45, v45, v49
	v_add_f32_e32 v27, v27, v45
	v_sub_f32_e32 v45, v47, v48
	v_add_f32_e32 v27, v45, v27
	v_add_f32_e32 v45, v50, v27
	v_mul_f32_e32 v47, v44, v45
	v_mul_f32_e32 v48, v26, v47
	v_fma_f32 v26, v47, v26, -v48
	v_fmac_f32_e32 v26, v47, v21
	v_sub_f32_e32 v21, v50, v45
	v_add_f32_e32 v21, v27, v21
	v_add_f32_e32 v27, v48, v26
	v_sub_f32_e32 v49, v45, v27
	v_sub_f32_e32 v45, v45, v49
	v_sub_f32_e32 v48, v27, v48
	v_sub_f32_e32 v27, v45, v27
	v_add_f32_e32 v21, v21, v27
	v_sub_f32_e32 v26, v48, v26
	v_add_f32_e32 v21, v26, v21
	v_add_f32_e32 v26, v46, v47
	v_add_f32_e32 v21, v49, v21
	v_sub_f32_e32 v27, v26, v46
; __device__ __forceinline__ float sigmoid_(float x) { return __builtin_amdgcn_rcpf(1.f + __expf(-x)); }
; __device__ __forceinline__ float softplus_(float x) { return fmaxf(x, 0.f) + log1pf(__expf(-fabsf(x))); }
; __device__ __forceinline__ unsigned f2bf(float f) { unsigned u = __builtin_bit_cast(unsigned, f); return (u + 0x7fffu + ((u >> 16) & 1u)) >> 16; }
; __device__ __forceinline__ void prep_phase(const Params& P, float* L, int l) {
;     ...
;             for (int jt = 0; jt < 4; ++jt) {
;                 const int j = jt * 16 + fr, c = h * 64 + j;
;                 const float ba1 = P.lru_ba[(size_t)(l * 2 + d) * 512 + c], bx1 = P.lru_bx[(size_t)(l * 2 + d) * 512 + c], sp = softplus_(-P.lru_lambda[(size_t)(l * 2 + d) * 512 + c]);
; #pragma unroll
;                 for (int jj = 0; jj < 4; ++jj) {
;                     const int t = tt * 16 + 4 * fq + jj, row = row0 + t;
;                     const float rg = sigmoid_(acc[0][jt][jj] + ba1), ig = sigmoid_(acc[1][jt][jj] + bx1);
;                     const float la = -8.f * rg * sp;
;                     const float a_ = __expf(la); LA[((size_t)d * MALL + row) * 512 + c] = a_;
;                     LB[((size_t)d * MALL + row) * 512 + c] = (bf16)f2bf(sqrtf(fmaxf(1.f - a_ * a_, 1e-12f)) * (ig * xs[t * 68 + j]));
;                 }
	v_mul_f32_e32 v21, v44, v21
	v_sub_f32_e32 v27, v47, v27
	v_add_f32_e32 v21, v27, v21
	v_mul_f32_e32 v46, 0x3f317218, v20
	v_add_f32_e32 v27, v26, v21
	v_fma_f32 v47, v20, s19, -v46
	v_mul_f32_e32 v44, v27, v27
	v_fmac_f32_e32 v47, 0xb102e308, v20
	v_sub_f32_e32 v20, v27, v26
	v_fmamk_f32 v45, v44, 0x3e9b6dac, v170
	v_sub_f32_e32 v20, v21, v20
	v_add_f32_e32 v21, v46, v47
	v_fmaak_f32 v45, v44, v45, 0x3f2aaada
	v_sub_f32_e32 v26, v21, v46
	v_ldexp_f32 v46, v27, 1
	v_mul_f32_e32 v27, v27, v44
	v_mul_f32_e32 v27, v27, v45
	v_add_f32_e32 v44, v46, v27
	v_sub_f32_e32 v45, v44, v46
	v_ldexp_f32 v20, v20, 1
	v_sub_f32_e32 v27, v27, v45
	v_add_f32_e32 v20, v20, v27
	v_add_f32_e32 v27, v44, v20
	v_sub_f32_e32 v44, v27, v44
	v_sub_f32_e32 v20, v20, v44
	v_add_f32_e32 v44, v21, v27
	v_sub_f32_e32 v26, v47, v26
	v_add_f32_e32 v27, v26, v20
	v_sub_f32_e32 v45, v27, v26
	v_rcp_f32_e32 v12, v12
	v_or_b32_e32 v26, v38, v2
	v_mul_f32_e32 v12, 0xc1000000, v12
	v_mov_b32_e32 v27, v39
	v_mul_f32_e32 v16, 0xbfb8aa3b, v16
	v_exp_f32_e32 v16, v16
	v_mov_b32_e32 v24, v110
	v_mul_f32_e32 v12, v12, v24
	v_mul_f32_e32 v12, 0x3fb8aa3b, v12
	v_exp_f32_e32 v12, v12
	v_lshl_add_u64 v[20:21], v[26:27], 2, s[0:1]
	v_add_f32_e32 v16, 1.0, v16
	v_rcp_f32_e32 v16, v16
	global_store_dword v[20:21], v12, off
	v_fma_f32 v12, -v12, v12, 1.0
	v_max_f32_e32 v12, 0x2b8cbccc, v12
	v_cmp_gt_f32_e32 vcc, s18, v12
	v_mul_f32_e32 v20, 0x4f800000, v12
	v_lshl_add_u64 v[26:27], v[26:27], 1, s[4:5]
	v_cndmask_b32_e32 v12, v12, v20, vcc
	v_sqrt_f32_e32 v20, v12
	s_nop 0
	v_add_u32_e32 v21, -1, v20
	v_fma_f32 v25, -v21, v20, v12
	v_cmp_ge_f32_e64 s[12:13], 0, v25
	v_add_u32_e32 v25, 1, v20
	s_nop 0
	v_cndmask_b32_e64 v21, v20, v21, s[12:13]
	v_fma_f32 v20, -v25, v20, v12
	v_cmp_lt_f32_e64 s[12:13], 0, v20
	s_nop 1
	v_cndmask_b32_e64 v20, v21, v25, s[12:13]
	v_mul_f32_e32 v21, 0x37800000, v20
	v_cndmask_b32_e32 v20, v20, v21, vcc
	v_cmp_class_f32_e32 vcc, v12, v171
	s_nop 1
	v_cndmask_b32_e32 v12, v20, v12, vcc
	ds_read2_b32 v[20:21], v66 offset0:32 offset1:48
	s_waitcnt lgkmcnt(0)
	v_mul_f32_e32 v16, v20, v16
	v_mul_f32_e32 v12, v16, v12
	v_bfe_u32 v16, v12, 16, 1
	v_add3_u32 v12, v12, v16, s71
	global_store_short_d16_hi v[26:27], v12, off
	v_add_f32_e32 v12, v13, v23
	v_mul_f32_e32 v12, 0xbfb8aa3b, v12
	v_exp_f32_e32 v12, v12
	v_add_f32_e32 v13, v17, v22
	v_mul_f32_e32 v13, 0xbfb8aa3b, v13
	v_exp_f32_e32 v13, v13
	v_add_f32_e32 v12, 1.0, v12
	v_rcp_f32_e32 v12, v12
	v_or_b32_e32 v16, v28, v2
	v_add_f32_e32 v13, 1.0, v13
	v_mov_b32_e32 v17, v29
	v_mul_f32_e32 v12, 0xc1000000, v12
	v_mul_f32_e32 v12, v12, v24
	v_mul_f32_e32 v12, 0x3fb8aa3b, v12
	v_exp_f32_e32 v25, v12
	v_rcp_f32_e32 v20, v13
	v_lshl_add_u64 v[12:13], v[16:17], 2, s[0:1]
	v_lshl_add_u64 v[16:17], v[16:17], 1, s[4:5]
	global_store_dword v[12:13], v25, off
	v_fma_f32 v12, -v25, v25, 1.0
	v_max_f32_e32 v12, 0x2b8cbccc, v12
	v_cmp_gt_f32_e32 vcc, s18, v12
	v_mul_f32_e32 v13, 0x4f800000, v12
	v_mov_b32_e32 v27, v33
	v_cndmask_b32_e32 v12, v12, v13, vcc
	v_sqrt_f32_e32 v13, v12
	s_nop 0
	v_add_u32_e32 v25, -1, v13
	v_fma_f32 v26, -v25, v13, v12
	v_cmp_ge_f32_e64 s[12:13], 0, v26
	v_add_u32_e32 v26, 1, v13
	s_nop 0
	v_cndmask_b32_e64 v25, v13, v25, s[12:13]
	v_fma_f32 v13, -v26, v13, v12
	v_cmp_lt_f32_e64 s[12:13], 0, v13
	s_nop 1
	v_cndmask_b32_e64 v13, v25, v26, s[12:13]
	v_mul_f32_e32 v25, 0x37800000, v13
	v_cndmask_b32_e32 v13, v13, v25, vcc
	v_cmp_class_f32_e32 vcc, v12, v171
	v_or_b32_e32 v26, v32, v2
	s_nop 0
	v_cndmask_b32_e32 v25, v13, v12, vcc
	ds_read2_b32 v[12:13], v66 offset0:100 offset1:116
	s_waitcnt lgkmcnt(0)
	v_mul_f32_e32 v12, v20, v12
	v_mul_f32_e32 v12, v12, v25
	v_bfe_u32 v20, v12, 16, 1
	v_add3_u32 v12, v12, v20, s71
	global_store_short_d16_hi v[16:17], v12, off
	v_add_f32_e32 v12, v14, v23
	v_mul_f32_e32 v12, 0xbfb8aa3b, v12
	v_exp_f32_e32 v12, v12
	v_lshl_add_u64 v[16:17], v[26:27], 2, s[0:1]
	v_add_f32_e32 v14, v18, v22
	v_mul_f32_e32 v14, 0xbfb8aa3b, v14
	v_add_f32_e32 v12, 1.0, v12
	v_rcp_f32_e32 v12, v12
	v_exp_f32_e32 v14, v14
	v_lshl_add_u64 v[26:27], v[26:27], 1, s[4:5]
	v_mul_f32_e32 v12, 0xc1000000, v12
	v_mul_f32_e32 v12, v12, v24
	v_mul_f32_e32 v12, 0x3fb8aa3b, v12
	v_exp_f32_e32 v12, v12
	v_add_f32_e32 v14, 1.0, v14
	v_rcp_f32_e32 v14, v14
	global_store_dword v[16:17], v12, off
	v_fma_f32 v12, -v12, v12, 1.0
	v_max_f32_e32 v12, 0x2b8cbccc, v12
	v_cmp_gt_f32_e32 vcc, s18, v12
	v_mul_f32_e32 v16, 0x4f800000, v12
	s_nop 0
	v_cndmask_b32_e32 v12, v12, v16, vcc
	v_sqrt_f32_e32 v16, v12
	s_nop 0
	v_add_u32_e32 v17, -1, v16
	v_fma_f32 v18, -v17, v16, v12
	v_cmp_ge_f32_e64 s[12:13], 0, v18
	v_add_u32_e32 v18, 1, v16
	s_nop 0
	v_cndmask_b32_e64 v17, v16, v17, s[12:13]
	v_fma_f32 v16, -v18, v16, v12
	v_cmp_lt_f32_e64 s[12:13], 0, v16
	s_nop 1
	v_cndmask_b32_e64 v16, v17, v18, s[12:13]
	v_mul_f32_e32 v17, 0x37800000, v16
	v_cndmask_b32_e32 v16, v16, v17, vcc
	v_cmp_class_f32_e32 vcc, v12, v171
	v_or_b32_e32 v18, v30, v2
	s_nop 0
	v_cndmask_b32_e32 v12, v16, v12, vcc
	ds_read2_b32 v[16:17], v66 offset0:168 offset1:184
	s_waitcnt lgkmcnt(0)
; __device__ __forceinline__ float sigmoid_(float x) { return __builtin_amdgcn_rcpf(1.f + __expf(-x)); }
; __device__ __forceinline__ float softplus_(float x) { return fmaxf(x, 0.f) + log1pf(__expf(-fabsf(x))); }
; __device__ __forceinline__ unsigned f2bf(float f) { unsigned u = __builtin_bit_cast(unsigned, f); return (u + 0x7fffu + ((u >> 16) & 1u)) >> 16; }
; __device__ __forceinline__ void prep_phase(const Params& P, float* L, int l) {
;     ...
;             for (int jt = 0; jt < 4; ++jt) {
;                 const int j = jt * 16 + fr, c = h * 64 + j;
;                 const float ba1 = P.lru_ba[(size_t)(l * 2 + d) * 512 + c], bx1 = P.lru_bx[(size_t)(l * 2 + d) * 512 + c], sp = softplus_(-P.lru_lambda[(size_t)(l * 2 + d) * 512 + c]);
; #pragma unroll
;                 for (int jj = 0; jj < 4; ++jj) {
;                     const int t = tt * 16 + 4 * fq + jj, row = row0 + t;
;                     const float rg = sigmoid_(acc[0][jt][jj] + ba1), ig = sigmoid_(acc[1][jt][jj] + bx1);
;                     const float la = -8.f * rg * sp;
;                     const float a_ = __expf(la); LA[((size_t)d * MALL + row) * 512 + c] = a_;
;                     LB[((size_t)d * MALL + row) * 512 + c] = (bf16)f2bf(sqrtf(fmaxf(1.f - a_ * a_, 1e-12f)) * (ig * xs[t * 68 + j]));
;                 }
	v_mul_f32_e32 v14, v14, v16
	v_mul_f32_e32 v12, v14, v12
	v_bfe_u32 v14, v12, 16, 1
	v_add3_u32 v12, v12, v14, s71
	global_store_short_d16_hi v[26:27], v12, off
	v_add_f32_e32 v12, v15, v23
	v_mul_f32_e32 v12, 0xbfb8aa3b, v12
	v_exp_f32_e32 v12, v12
	v_add_f32_e32 v14, v19, v22
	v_mul_f32_e32 v14, 0xbfb8aa3b, v14
	v_exp_f32_e32 v14, v14
	v_add_f32_e32 v12, 1.0, v12
	v_rcp_f32_e32 v12, v12
	v_mov_b32_e32 v19, v31
	v_add_f32_e32 v14, 1.0, v14
	v_rcp_f32_e32 v16, v14
	v_mul_f32_e32 v12, 0xc1000000, v12
	v_mul_f32_e32 v12, v12, v24
	v_mul_f32_e32 v12, 0x3fb8aa3b, v12
	v_exp_f32_e32 v12, v12
	v_lshl_add_u64 v[14:15], v[18:19], 2, s[0:1]
	v_lshl_add_u64 v[18:19], v[18:19], 1, s[4:5]
	v_fma_f32 v2, -v12, v12, 1.0
	v_max_f32_e32 v2, 0x2b8cbccc, v2
	global_store_dword v[14:15], v12, off
	v_cmp_gt_f32_e32 vcc, s18, v2
	v_mul_f32_e32 v12, 0x4f800000, v2
	s_nop 0
	v_cndmask_b32_e32 v2, v2, v12, vcc
	v_sqrt_f32_e32 v12, v2
	s_nop 0
	v_add_u32_e32 v14, -1, v12
	v_fma_f32 v15, -v14, v12, v2
	v_cmp_ge_f32_e64 s[12:13], 0, v15
	v_add_u32_e32 v15, 1, v12
	s_nop 0
	v_cndmask_b32_e64 v14, v12, v14, s[12:13]
	v_fma_f32 v12, -v15, v12, v2
	v_cmp_lt_f32_e64 s[12:13], 0, v12
	s_nop 1
	v_cndmask_b32_e64 v12, v14, v15, s[12:13]
	v_mul_f32_e32 v14, 0x37800000, v12
	v_cndmask_b32_e32 v12, v12, v14, vcc
	ds_read2_b32 v[14:15], v66 offset0:236 offset1:252
	v_cmp_class_f32_e32 vcc, v2, v171
	s_nop 1
	v_cndmask_b32_e32 v2, v12, v2, vcc
	s_waitcnt lgkmcnt(0)
	v_mul_f32_e32 v12, v16, v14
	v_mul_f32_e32 v2, v12, v2
	v_bfe_u32 v12, v2, 16, 1
	v_add3_u32 v2, v2, v12, s71
	global_store_short_d16_hi v[18:19], v2, off
	global_load_dword v14, v[40:41], off offset:192
	global_load_dword v12, v[42:43], off offset:192
	s_nop 0
	global_load_dword v18, v[34:35], off offset:192
	v_or_b32_e32 v2, s58, v61
	v_or_b32_e32 v38, v38, v2
	v_or_b32_e32 v28, v28, v2
	v_or_b32_e32 v32, v32, v2
	v_or_b32_e32 v30, v30, v2
	s_waitcnt vmcnt(2)
	v_add_f32_e32 v4, v4, v14
	v_mul_f32_e32 v4, 0xbfb8aa3b, v4
	s_waitcnt vmcnt(0)
	v_mul_f32_e64 v18, |v18|, s16
	v_exp_f32_e32 v20, v18
	v_exp_f32_e32 v4, v4
	v_add_f32_e32 v8, v8, v12
	v_add_f32_e32 v22, 1.0, v20
	v_add_f32_e32 v18, -1.0, v22
	v_sub_f32_e32 v19, v18, v22
	v_add_f32_e32 v19, 1.0, v19
	v_sub_f32_e32 v18, v20, v18
	v_add_f32_e32 v23, v18, v19
	v_frexp_mant_f32_e32 v18, v22
	v_cmp_gt_f32_e32 vcc, s17, v18
	v_cvt_f64_f32_e32 v[18:19], v22
	v_frexp_exp_i32_f64_e32 v18, v[18:19]
	v_subbrev_co_u32_e32 v18, vcc, 0, v18, vcc
	v_sub_u32_e32 v19, 0, v18
	v_ldexp_f32 v22, v22, v19
	v_ldexp_f32 v19, v23, v19
	v_add_f32_e32 v23, -1.0, v22
	v_add_f32_e32 v24, 1.0, v23
	v_sub_f32_e32 v24, v22, v24
	v_add_f32_e32 v24, v19, v24
	v_add_f32_e32 v25, v23, v24
	v_sub_f32_e32 v23, v25, v23
	v_sub_f32_e32 v23, v24, v23
	v_add_f32_e32 v24, 1.0, v22
	v_add_f32_e32 v26, -1.0, v24
	v_sub_f32_e32 v22, v22, v26
	v_add_f32_e32 v19, v19, v22
	v_add_f32_e32 v22, v24, v19
	v_sub_f32_e32 v24, v22, v24
	v_sub_f32_e32 v19, v19, v24
	v_rcp_f32_e32 v24, v22
	v_cvt_f32_i32_e32 v18, v18
	v_add_f32_e32 v4, 1.0, v4
	v_mul_f32_e32 v26, v25, v24
	v_mul_f32_e32 v27, v22, v26
	v_fma_f32 v34, v26, v22, -v27
	v_fmac_f32_e32 v34, v26, v19
	v_add_f32_e32 v35, v27, v34
	v_sub_f32_e32 v40, v25, v35
	v_sub_f32_e32 v25, v25, v40
	v_sub_f32_e32 v27, v35, v27
	v_sub_f32_e32 v25, v25, v35
	v_add_f32_e32 v23, v23, v25
	v_sub_f32_e32 v25, v27, v34
	v_add_f32_e32 v23, v25, v23
	v_add_f32_e32 v25, v40, v23
	v_mul_f32_e32 v27, v24, v25
	v_mul_f32_e32 v34, v22, v27
	v_fma_f32 v22, v27, v22, -v34
	v_fmac_f32_e32 v22, v27, v19
	v_sub_f32_e32 v19, v40, v25
	v_add_f32_e32 v19, v23, v19
	v_add_f32_e32 v23, v34, v22
	v_sub_f32_e32 v35, v25, v23
	v_sub_f32_e32 v25, v25, v35
	v_sub_f32_e32 v34, v23, v34
	v_sub_f32_e32 v23, v25, v23
	v_add_f32_e32 v19, v19, v23
	v_sub_f32_e32 v22, v34, v22
	v_add_f32_e32 v19, v22, v19
	v_add_f32_e32 v22, v26, v27
	v_add_f32_e32 v19, v35, v19
	v_sub_f32_e32 v23, v22, v26
	v_mul_f32_e32 v19, v24, v19
	v_sub_f32_e32 v23, v27, v23
	v_add_f32_e32 v19, v23, v19
	v_mul_f32_e32 v26, 0x3f317218, v18
	v_add_f32_e32 v23, v22, v19
	v_fma_f32 v27, v18, s19, -v26
	v_mul_f32_e32 v24, v23, v23
	v_fmac_f32_e32 v27, 0xb102e308, v18
	v_sub_f32_e32 v18, v23, v22
	v_fmamk_f32 v25, v24, 0x3e9b6dac, v170
	v_sub_f32_e32 v18, v19, v18
	v_add_f32_e32 v19, v26, v27
	v_fmaak_f32 v25, v24, v25, 0x3f2aaada
	v_sub_f32_e32 v22, v19, v26
	v_ldexp_f32 v26, v23, 1
	v_mul_f32_e32 v23, v23, v24
	v_mul_f32_e32 v23, v23, v25
	v_add_f32_e32 v24, v26, v23
	v_sub_f32_e32 v25, v24, v26
	v_ldexp_f32 v18, v18, 1
	v_sub_f32_e32 v23, v23, v25
	v_add_f32_e32 v18, v18, v23
	v_add_f32_e32 v23, v24, v18
	v_sub_f32_e32 v24, v23, v24
	v_sub_f32_e32 v18, v18, v24
	v_add_f32_e32 v24, v19, v23
	v_sub_f32_e32 v25, v24, v19
	v_sub_f32_e32 v26, v24, v25
	v_sub_f32_e32 v22, v27, v22
	v_sub_f32_e32 v19, v19, v26
	v_sub_f32_e32 v23, v23, v25
	v_add_f32_e32 v19, v23, v19
	v_add_f32_e32 v23, v22, v18
	v_sub_f32_e32 v25, v23, v22
	v_sub_f32_e32 v26, v23, v25
	v_add_f32_e32 v19, v23, v19
	v_add_f32_e32 v22, v24, v19
	v_sub_f32_e32 v23, v22, v24
	v_rcp_f32_e32 v4, v4
	v_mul_f32_e32 v8, 0xbfb8aa3b, v8
	v_mul_f32_e32 v4, 0xc1000000, v4
	v_exp_f32_e32 v8, v8
	s_nop 0
	v_add_f32_e32 v8, 1.0, v8
	s_nop 0
	v_mov_b32_e32 v16, v111
	v_mul_f32_e32 v4, v4, v16
	v_mul_f32_e32 v4, 0x3fb8aa3b, v4
	v_exp_f32_e32 v4, v4
	v_lshl_add_u64 v[18:19], v[38:39], 2, s[0:1]
	v_rcp_f32_e32 v8, v8
	global_store_dword v[18:19], v4, off
	v_fma_f32 v4, -v4, v4, 1.0
	v_max_f32_e32 v4, 0x2b8cbccc, v4
	v_cmp_gt_f32_e32 vcc, s18, v4
	v_mul_f32_e32 v18, 0x4f800000, v4
	v_mul_f32_e32 v8, v21, v8
	v_cndmask_b32_e32 v4, v4, v18, vcc
	v_sqrt_f32_e32 v18, v4
	s_nop 0
; __device__ __forceinline__ float sigmoid_(float x) { return __builtin_amdgcn_rcpf(1.f + __expf(-x)); }
; __device__ __forceinline__ float softplus_(float x) { return fmaxf(x, 0.f) + log1pf(__expf(-fabsf(x))); }
; __device__ __forceinline__ unsigned f2bf(float f) { unsigned u = __builtin_bit_cast(unsigned, f); return (u + 0x7fffu + ((u >> 16) & 1u)) >> 16; }
; __device__ __forceinline__ int bid_() { int t = blockIdx.x; asm volatile("" : "+s"(t)); return t; }
; __device__ __forceinline__ void prep_phase(const Params& P, float* L, int l) {
;     ...
;     for (int it = bid_(); it < 144 * 8; it += gridDim.x) {
;         const int h = it & 7, row0 = (it >> 3) * 64;
;         __syncthreads();
;         if (h != cur_h) {
;             for (int i = tid; i < 4 * 4096; i += 512) { const int m = i >> 12, ii = (i >> 6) & 63, j = i & 63, d = m >> 1; const float* src = (m & 1) ? P.lru_wx : P.lru_wa;
;                 WT[(m * 64 + j) * 72 + ii] = (unsigned short)f2bf(src[((size_t)(l * 2 + d) * 8 + h) * 4096 + ii * 64 + j]); }
;             cur_h = h;
;     ...
;             for (int jt = 0; jt < 4; ++jt) {
;                 const int j = jt * 16 + fr, c = h * 64 + j;
;                 const float ba1 = P.lru_ba[(size_t)(l * 2 + d) * 512 + c], bx1 = P.lru_bx[(size_t)(l * 2 + d) * 512 + c], sp = softplus_(-P.lru_lambda[(size_t)(l * 2 + d) * 512 + c]);
; #pragma unroll
;                 for (int jj = 0; jj < 4; ++jj) {
;                     const int t = tt * 16 + 4 * fq + jj, row = row0 + t;
;                     const float rg = sigmoid_(acc[0][jt][jj] + ba1), ig = sigmoid_(acc[1][jt][jj] + bx1);
;                     const float la = -8.f * rg * sp;
;                     const float a_ = __expf(la); LA[((size_t)d * MALL + row) * 512 + c] = a_;
;                     LB[((size_t)d * MALL + row) * 512 + c] = (bf16)f2bf(sqrtf(fmaxf(1.f - a_ * a_, 1e-12f)) * (ig * xs[t * 68 + j]));
;                 }
	v_add_u32_e32 v19, -1, v18
	v_fma_f32 v20, -v19, v18, v4
	v_cmp_ge_f32_e64 s[12:13], 0, v20
	v_add_u32_e32 v20, 1, v18
	s_nop 0
	v_cndmask_b32_e64 v19, v18, v19, s[12:13]
	v_fma_f32 v18, -v20, v18, v4
	v_cmp_lt_f32_e64 s[12:13], 0, v18
	s_nop 1
	v_cndmask_b32_e64 v18, v19, v20, s[12:13]
	v_mul_f32_e32 v19, 0x37800000, v18
	v_cndmask_b32_e32 v18, v18, v19, vcc
	v_cmp_class_f32_e32 vcc, v4, v171
	s_nop 1
	v_cndmask_b32_e32 v4, v18, v4, vcc
	v_mul_f32_e32 v4, v8, v4
	v_bfe_u32 v8, v4, 16, 1
	v_add3_u32 v4, v4, v8, s71
	v_lshl_add_u64 v[18:19], v[38:39], 1, s[4:5]
	global_store_short_d16_hi v[18:19], v4, off
	v_add_f32_e32 v4, v5, v14
	v_mul_f32_e32 v4, 0xbfb8aa3b, v4
	v_exp_f32_e32 v4, v4
	v_add_f32_e32 v5, v9, v12
	v_mul_f32_e32 v5, 0xbfb8aa3b, v5
	v_exp_f32_e32 v5, v5
	v_add_f32_e32 v4, 1.0, v4
	v_rcp_f32_e32 v4, v4
	v_add_f32_e32 v5, 1.0, v5
	v_rcp_f32_e32 v8, v5
	v_mul_f32_e32 v4, 0xc1000000, v4
	v_mul_f32_e32 v4, v4, v16
	v_mul_f32_e32 v4, 0x3fb8aa3b, v4
	v_exp_f32_e32 v9, v4
	v_lshl_add_u64 v[4:5], v[28:29], 2, s[0:1]
	global_store_dword v[4:5], v9, off
	v_fma_f32 v4, -v9, v9, 1.0
	v_max_f32_e32 v4, 0x2b8cbccc, v4
	v_cmp_gt_f32_e32 vcc, s18, v4
	v_mul_f32_e32 v5, 0x4f800000, v4
	s_nop 0
	v_cndmask_b32_e32 v4, v4, v5, vcc
	v_sqrt_f32_e32 v5, v4
	s_nop 0
	v_add_u32_e32 v9, -1, v5
	v_fma_f32 v18, -v9, v5, v4
	v_cmp_ge_f32_e64 s[12:13], 0, v18
	v_add_u32_e32 v18, 1, v5
	s_nop 0
	v_cndmask_b32_e64 v9, v5, v9, s[12:13]
	v_fma_f32 v5, -v18, v5, v4
	v_cmp_lt_f32_e64 s[12:13], 0, v5
	s_nop 1
	v_cndmask_b32_e64 v5, v9, v18, s[12:13]
	v_mul_f32_e32 v9, 0x37800000, v5
	v_cndmask_b32_e32 v5, v5, v9, vcc
	v_cmp_class_f32_e32 vcc, v4, v171
	s_nop 1
	v_cndmask_b32_e32 v4, v5, v4, vcc
	v_mul_f32_e32 v5, v8, v13
	v_mul_f32_e32 v4, v5, v4
	v_bfe_u32 v5, v4, 16, 1
	v_add3_u32 v8, v4, v5, s71
	v_lshl_add_u64 v[4:5], v[28:29], 1, s[4:5]
	global_store_short_d16_hi v[4:5], v8, off
	v_add_f32_e32 v4, v6, v14
	v_mul_f32_e32 v4, 0xbfb8aa3b, v4
	v_exp_f32_e32 v4, v4
	v_add_f32_e32 v5, v10, v12
	v_mul_f32_e32 v5, 0xbfb8aa3b, v5
	v_exp_f32_e32 v5, v5
	v_add_f32_e32 v4, 1.0, v4
	v_rcp_f32_e32 v4, v4
	v_add_f32_e32 v5, 1.0, v5
	v_rcp_f32_e32 v6, v5
	v_mul_f32_e32 v4, 0xc1000000, v4
	v_mul_f32_e32 v4, v4, v16
	v_mul_f32_e32 v4, 0x3fb8aa3b, v4
	v_exp_f32_e32 v8, v4
	v_lshl_add_u64 v[4:5], v[32:33], 2, s[0:1]
	global_store_dword v[4:5], v8, off
	v_fma_f32 v4, -v8, v8, 1.0
	v_max_f32_e32 v4, 0x2b8cbccc, v4
	v_cmp_gt_f32_e32 vcc, s18, v4
	v_mul_f32_e32 v5, 0x4f800000, v4
	s_nop 0
	v_cndmask_b32_e32 v4, v4, v5, vcc
	v_sqrt_f32_e32 v5, v4
	s_nop 0
	v_add_u32_e32 v8, -1, v5
	v_fma_f32 v9, -v8, v5, v4
	v_cmp_ge_f32_e64 s[12:13], 0, v9
	v_add_u32_e32 v9, 1, v5
	s_nop 0
	v_cndmask_b32_e64 v8, v5, v8, s[12:13]
	v_fma_f32 v5, -v9, v5, v4
	v_cmp_lt_f32_e64 s[12:13], 0, v5
	s_nop 1
	v_cndmask_b32_e64 v5, v8, v9, s[12:13]
	v_mul_f32_e32 v8, 0x37800000, v5
	v_cndmask_b32_e32 v5, v5, v8, vcc
	v_cmp_class_f32_e32 vcc, v4, v171
	s_nop 1
	v_cndmask_b32_e32 v4, v5, v4, vcc
	v_mul_f32_e32 v5, v6, v17
	v_mul_f32_e32 v4, v5, v4
	v_bfe_u32 v5, v4, 16, 1
	v_add3_u32 v6, v4, v5, s71
	v_lshl_add_u64 v[4:5], v[32:33], 1, s[4:5]
	global_store_short_d16_hi v[4:5], v6, off
	v_add_f32_e32 v4, v7, v14
	v_mul_f32_e32 v4, 0xbfb8aa3b, v4
	v_exp_f32_e32 v4, v4
	v_add_f32_e32 v5, v11, v12
	v_mul_f32_e32 v5, 0xbfb8aa3b, v5
	v_exp_f32_e32 v5, v5
	v_add_f32_e32 v4, 1.0, v4
	v_rcp_f32_e32 v4, v4
	v_add_f32_e32 v5, 1.0, v5
	v_rcp_f32_e32 v6, v5
	v_mul_f32_e32 v4, 0xc1000000, v4
	v_mul_f32_e32 v4, v4, v16
	v_mul_f32_e32 v4, 0x3fb8aa3b, v4
	v_exp_f32_e32 v7, v4
	v_lshl_add_u64 v[4:5], v[30:31], 2, s[0:1]
	v_fma_f32 v2, -v7, v7, 1.0
	v_max_f32_e32 v2, 0x2b8cbccc, v2
	global_store_dword v[4:5], v7, off
	v_cmp_gt_f32_e32 vcc, s18, v2
	v_mul_f32_e32 v4, 0x4f800000, v2
	s_nop 0
	v_cndmask_b32_e32 v2, v2, v4, vcc
	v_sqrt_f32_e32 v4, v2
	s_nop 0
	v_add_u32_e32 v5, -1, v4
	v_fma_f32 v7, -v5, v4, v2
	v_cmp_ge_f32_e64 s[12:13], 0, v7
	v_add_u32_e32 v7, 1, v4
	s_nop 0
	v_cndmask_b32_e64 v5, v4, v5, s[12:13]
	v_fma_f32 v4, -v7, v4, v2
	v_cmp_lt_f32_e64 s[12:13], 0, v4
	s_nop 1
	v_cndmask_b32_e64 v4, v5, v7, s[12:13]
	v_mul_f32_e32 v5, 0x37800000, v4
	v_cndmask_b32_e32 v4, v4, v5, vcc
	v_cmp_class_f32_e32 vcc, v2, v171
	v_readlane_b32 s12, v254, 18
	v_readlane_b32 s13, v254, 19
	v_cndmask_b32_e32 v2, v4, v2, vcc
	v_mul_f32_e32 v4, v6, v15
	v_mul_f32_e32 v2, v4, v2
	v_bfe_u32 v4, v2, 16, 1
	v_add3_u32 v2, v2, v4, s71
	v_lshl_add_u64 v[4:5], v[30:31], 1, s[4:5]
	global_store_short_d16_hi v[4:5], v2, off
	s_load_dword s12, s[12:13], 0x0
	s_waitcnt lgkmcnt(0)
	s_add_i32 s34, s34, s12
	s_cmpk_gt_i32 s34, 0x47f
.Lprepe_join:
	s_cbranch_scc1 .LBB0_278
.LBB0_259:
	s_mov_b32 s12, s68
	s_and_b32 s68, s34, 7
	s_cmp_lg_u32 s68, s12
	s_cselect_b32 s101, 1, 0
	s_cselect_b64 s[12:13], -1, 0
	s_and_b64 s[12:13], s[96:97], s[12:13]
	s_waitcnt lgkmcnt(0)
	s_barrier
	s_and_saveexec_b64 s[24:25], s[12:13]
	v_readlane_b32 s36, v254, 62
	v_readlane_b32 s37, v254, 63
	v_readlane_b32 s38, v255, 0
	v_readlane_b32 s39, v255, 1
	v_readlane_b32 s40, v255, 2
	v_readlane_b32 s41, v255, 3
	v_readlane_b32 s42, v255, 4
	v_readlane_b32 s43, v255, 5
	v_readlane_b32 s44, v255, 6
	v_readlane_b32 s45, v255, 7
	v_readlane_b32 s46, v255, 8
	v_readlane_b32 s47, v255, 9
	v_readlane_b32 s48, v255, 10
	v_readlane_b32 s49, v255, 11
	v_readlane_b32 s50, v255, 12
	v_readlane_b32 s51, v255, 13
	s_cbranch_execz .LBB0_267
	v_readlane_b32 s16, v255, 33
	s_lshl_b32 s30, s68, 12
	s_mov_b64 s[12:13], -1
	v_mov_b32_e32 v4, v0
	v_readlane_b32 s17, v255, 34
	s_and_saveexec_b64 s[26:27], s[16:17]
	s_cbranch_execz .LBB0_264
	v_readlane_b32 s36, v254, 62
	v_readlane_b32 s46, v255, 8
	v_readlane_b32 s47, v255, 9
	s_mov_b64 s[28:29], 0
	v_mov_b32_e32 v6, v62
	v_mov_b64_e32 v[4:5], v[0:1]
	s_mov_b64 s[62:63], s[46:47]
	v_readlane_b32 s37, v254, 63
	v_readlane_b32 s38, v255, 0
	v_readlane_b32 s39, v255, 1
	v_readlane_b32 s40, v255, 2
	v_readlane_b32 s41, v255, 3
	v_readlane_b32 s42, v255, 4
	v_readlane_b32 s43, v255, 5
	v_readlane_b32 s44, v255, 6
	v_readlane_b32 s45, v255, 7
	v_readlane_b32 s48, v255, 10
	v_readlane_b32 s49, v255, 11
	v_readlane_b32 s50, v255, 12
	v_readlane_b32 s51, v255, 13
